# GEMM loops: per-phase setprio flips deleted, one static s_setprio 1 for waves 4-7 around each K loop
# baseline (speedup 1.0000x reference)
.LBB0_158:
	s_ashr_i32 s19, s18, 31
	s_lshl_b64 s[28:29], s[18:19], 20
	s_add_u32 s28, s21, s28
	s_addc_u32 s29, s23, s29
	s_and_b64 s[30:31], s[2:3], exec
	s_cselect_b32 s19, s29, s37
	s_cselect_b32 s55, s28, s36
	s_ashr_i32 s17, s16, 31
	s_lshl_b64 s[30:31], s[16:17], 20
	s_add_u32 s30, s24, s30
	s_addc_u32 s31, s25, s31
	s_and_b64 s[40:41], s[2:3], exec
	s_cselect_b32 s17, s31, s39
	s_cselect_b32 s56, s30, s38
	s_add_u32 s57, s38, 0x100
	v_mov_b32_e32 v0, 0
	s_addc_u32 s58, s39, 0
	s_mov_b32 s59, -2
	v_mov_b32_e32 v1, v0
	v_mov_b32_e32 v2, v0
	v_mov_b32_e32 v3, v0
	v_mov_b32_e32 v4, v0
	v_mov_b32_e32 v5, v0
	v_mov_b32_e32 v6, v0
	v_mov_b32_e32 v7, v0
	v_mov_b32_e32 v16, v0
	v_mov_b32_e32 v17, v0
	v_mov_b32_e32 v18, v0
	v_mov_b32_e32 v19, v0
	v_mov_b32_e32 v20, v0
	v_mov_b32_e32 v21, v0
	v_mov_b32_e32 v22, v0
	v_mov_b32_e32 v23, v0
	v_mov_b32_e32 v32, v0
	v_mov_b32_e32 v33, v0
	v_mov_b32_e32 v34, v0
	v_mov_b32_e32 v35, v0
	v_mov_b32_e32 v36, v0
	v_mov_b32_e32 v37, v0
	v_mov_b32_e32 v38, v0
	v_mov_b32_e32 v39, v0
	v_mov_b32_e32 v48, v0
	v_mov_b32_e32 v49, v0
	v_mov_b32_e32 v50, v0
	v_mov_b32_e32 v51, v0
	v_mov_b32_e32 v52, v0
	v_mov_b32_e32 v53, v0
	v_mov_b32_e32 v54, v0
	v_mov_b32_e32 v55, v0
	v_mov_b32_e32 v8, v0
	v_mov_b32_e32 v9, v0
	v_mov_b32_e32 v10, v0
	v_mov_b32_e32 v11, v0
	v_mov_b32_e32 v12, v0
	v_mov_b32_e32 v13, v0
	v_mov_b32_e32 v14, v0
	v_mov_b32_e32 v15, v0
	v_mov_b32_e32 v24, v0
	v_mov_b32_e32 v25, v0
	v_mov_b32_e32 v26, v0
	v_mov_b32_e32 v27, v0
	v_mov_b32_e32 v28, v0
	v_mov_b32_e32 v29, v0
	v_mov_b32_e32 v30, v0
	v_mov_b32_e32 v31, v0
	v_mov_b32_e32 v40, v0
	v_mov_b32_e32 v41, v0
	v_mov_b32_e32 v42, v0
	v_mov_b32_e32 v43, v0
	v_mov_b32_e32 v44, v0
	v_mov_b32_e32 v45, v0
	v_mov_b32_e32 v46, v0
	v_mov_b32_e32 v47, v0
	v_mov_b32_e32 v56, v0
	v_mov_b32_e32 v57, v0
	v_mov_b32_e32 v58, v0
	v_mov_b32_e32 v59, v0
	v_mov_b32_e32 v60, v0
	v_mov_b32_e32 v61, v0
	v_mov_b32_e32 v62, v0
	v_mov_b32_e32 v63, v0
	v_mov_b32_e32 v64, v0
	v_mov_b32_e32 v65, v0
	v_mov_b32_e32 v66, v0
	v_mov_b32_e32 v67, v0
	v_mov_b32_e32 v68, v0
	v_mov_b32_e32 v69, v0
	v_mov_b32_e32 v70, v0
	v_mov_b32_e32 v71, v0
	v_mov_b32_e32 v80, v0
	v_mov_b32_e32 v81, v0
	v_mov_b32_e32 v82, v0
	v_mov_b32_e32 v83, v0
	v_mov_b32_e32 v84, v0
	v_mov_b32_e32 v85, v0
	v_mov_b32_e32 v86, v0
	v_mov_b32_e32 v87, v0
	v_mov_b32_e32 v96, v0
	v_mov_b32_e32 v97, v0
	v_mov_b32_e32 v98, v0
	v_mov_b32_e32 v99, v0
	v_mov_b32_e32 v100, v0
	v_mov_b32_e32 v101, v0
	v_mov_b32_e32 v102, v0
	v_mov_b32_e32 v103, v0
	v_mov_b32_e32 v112, v0
	v_mov_b32_e32 v113, v0
	v_mov_b32_e32 v114, v0
	v_mov_b32_e32 v115, v0
	v_mov_b32_e32 v116, v0
	v_mov_b32_e32 v117, v0
	v_mov_b32_e32 v118, v0
	v_mov_b32_e32 v119, v0
	v_mov_b32_e32 v72, v0
	v_mov_b32_e32 v73, v0
	v_mov_b32_e32 v74, v0
	v_mov_b32_e32 v75, v0
	v_mov_b32_e32 v76, v0
	v_mov_b32_e32 v77, v0
	v_mov_b32_e32 v78, v0
	v_mov_b32_e32 v79, v0
	v_mov_b32_e32 v88, v0
	v_mov_b32_e32 v89, v0
	v_mov_b32_e32 v90, v0
	v_mov_b32_e32 v91, v0
	v_mov_b32_e32 v92, v0
	v_mov_b32_e32 v93, v0
	v_mov_b32_e32 v94, v0
	v_mov_b32_e32 v95, v0
	v_mov_b32_e32 v104, v0
	v_mov_b32_e32 v105, v0
	v_mov_b32_e32 v106, v0
	v_mov_b32_e32 v107, v0
	v_mov_b32_e32 v108, v0
	v_mov_b32_e32 v109, v0
	v_mov_b32_e32 v110, v0
	v_mov_b32_e32 v111, v0
	v_mov_b32_e32 v120, v0
	v_mov_b32_e32 v121, v0
	v_mov_b32_e32 v122, v0
	v_mov_b32_e32 v123, v0
	v_mov_b32_e32 v124, v0
	v_mov_b32_e32 v125, v0
	v_mov_b32_e32 v126, v0
	v_mov_b32_e32 v127, v0
	s_cmp_lt_u32 s97, 4
	s_cbranch_scc1 .Lgprio0
	s_setprio 1
.Lgprio0:
.LBB0_159:
	ds_read_b128 v[150:153], v147
	ds_read_b128 v[154:157], v147 offset:1024
	ds_read_b128 v[158:161], v147 offset:2048
	ds_read_b128 v[162:165], v147 offset:3072
	ds_read_b128 v[166:169], v148
	ds_read_b128 v[170:173], v148 offset:1024
	ds_read_b128 v[174:177], v148 offset:2048
	ds_read_b128 v[178:181], v148 offset:3072
	s_add_u32 s38, s36, 0x100
	s_addc_u32 s39, s37, 0
	s_cmp_eq_u32 s59, 28
	s_cselect_b32 s43, s19, s39
	s_cselect_b32 s42, s55, s38
	s_cselect_b32 s41, s17, s58
	s_cselect_b32 s40, s56, s57
	v_lshl_add_u64 v[182:183], s[36:37], 0, v[136:137]
	s_add_i32 m0, s35, 0xc000
	s_nop 0
	global_load_lds_dwordx4 v[182:183], off
	v_lshl_add_u64 v[182:183], s[36:37], 0, v[138:139]
	s_add_i32 m0, s35, 0xe000
	s_nop 0
	global_load_lds_dwordx4 v[182:183], off
	ds_read_b128 v[182:185], v149
	ds_read_b128 v[186:189], v149 offset:1024
	ds_read_b128 v[190:193], v149 offset:2048
	ds_read_b128 v[194:197], v149 offset:3072
	ds_read_b128 v[198:201], v149 offset:4096
	ds_read_b128 v[202:205], v149 offset:5120
	ds_read_b128 v[206:209], v149 offset:6144
	ds_read_b128 v[210:213], v149 offset:7168
	s_waitcnt vmcnt(8)
	s_waitcnt lgkmcnt(0)
	s_barrier
	s_waitcnt lgkmcnt(0)
	v_mfma_f32_16x16x32_bf16 v[124:127], v[150:153], v[182:185], v[124:127]
	v_mfma_f32_16x16x32_bf16 v[120:123], v[158:161], v[182:185], v[120:123]
	v_mfma_f32_16x16x32_bf16 v[108:111], v[150:153], v[190:193], v[108:111]
	v_mfma_f32_16x16x32_bf16 v[104:107], v[158:161], v[190:193], v[104:107]
	v_mfma_f32_16x16x32_bf16 v[92:95], v[150:153], v[198:201], v[92:95]
	v_mfma_f32_16x16x32_bf16 v[88:91], v[158:161], v[198:201], v[88:91]
	v_mfma_f32_16x16x32_bf16 v[76:79], v[150:153], v[206:209], v[76:79]
	v_mfma_f32_16x16x32_bf16 v[72:75], v[158:161], v[206:209], v[72:75]
	v_mfma_f32_16x16x32_bf16 v[124:127], v[154:157], v[186:189], v[124:127]
	v_mfma_f32_16x16x32_bf16 v[120:123], v[162:165], v[186:189], v[120:123]
	v_mfma_f32_16x16x32_bf16 v[108:111], v[154:157], v[194:197], v[108:111]
	v_mfma_f32_16x16x32_bf16 v[104:107], v[162:165], v[194:197], v[104:107]
	v_mfma_f32_16x16x32_bf16 v[92:95], v[154:157], v[202:205], v[92:95]
	v_mfma_f32_16x16x32_bf16 v[88:91], v[162:165], v[202:205], v[88:91]
	v_mfma_f32_16x16x32_bf16 v[76:79], v[154:157], v[210:213], v[76:79]
	v_mfma_f32_16x16x32_bf16 v[72:75], v[162:165], v[210:213], v[72:75]
	v_mfma_f32_16x16x32_bf16 v[116:119], v[166:169], v[182:185], v[116:119]
	v_mfma_f32_16x16x32_bf16 v[112:115], v[174:177], v[182:185], v[112:115]
	v_mfma_f32_16x16x32_bf16 v[100:103], v[166:169], v[190:193], v[100:103]
	v_mfma_f32_16x16x32_bf16 v[96:99], v[174:177], v[190:193], v[96:99]
	v_mfma_f32_16x16x32_bf16 v[84:87], v[166:169], v[198:201], v[84:87]
	v_mfma_f32_16x16x32_bf16 v[80:83], v[174:177], v[198:201], v[80:83]
	v_mfma_f32_16x16x32_bf16 v[68:71], v[166:169], v[206:209], v[68:71]
	v_mfma_f32_16x16x32_bf16 v[64:67], v[174:177], v[206:209], v[64:67]
	v_mfma_f32_16x16x32_bf16 v[116:119], v[170:173], v[186:189], v[116:119]
	v_mfma_f32_16x16x32_bf16 v[112:115], v[178:181], v[186:189], v[112:115]
	v_mfma_f32_16x16x32_bf16 v[100:103], v[170:173], v[194:197], v[100:103]
	v_mfma_f32_16x16x32_bf16 v[96:99], v[178:181], v[194:197], v[96:99]
	v_mfma_f32_16x16x32_bf16 v[84:87], v[170:173], v[202:205], v[84:87]
	v_mfma_f32_16x16x32_bf16 v[80:83], v[178:181], v[202:205], v[80:83]
	v_mfma_f32_16x16x32_bf16 v[68:71], v[170:173], v[210:213], v[68:71]
	v_mfma_f32_16x16x32_bf16 v[64:67], v[178:181], v[210:213], v[64:67]
	s_barrier
	s_add_i32 s36, s51, s11
	v_lshl_add_u64 v[214:215], s[40:41], 0, v[130:131]
	s_mov_b32 m0, s36
	v_lshl_add_u64 v[216:217], s[40:41], 0, v[134:135]
	global_load_lds_dwordx4 v[214:215], off
	s_add_i32 m0, s36, 0x2000
	s_add_u32 s36, s40, 0x80000
	s_addc_u32 s37, s41, 0
	s_add_i32 s60, s52, s11
	global_load_lds_dwordx4 v[216:217], off
	v_lshl_add_u64 v[182:183], s[36:37], 0, v[130:131]
	s_mov_b32 m0, s60
	v_lshl_add_u64 v[218:219], s[42:43], 0, v[128:129]
	global_load_lds_dwordx4 v[182:183], off
	v_lshl_add_u64 v[182:183], s[36:37], 0, v[134:135]
	s_add_i32 m0, s60, 0x2000
	v_lshl_add_u64 v[220:221], s[42:43], 0, v[132:133]
	global_load_lds_dwordx4 v[182:183], off
	s_mov_b32 m0, s35
	s_nop 0
	global_load_lds_dwordx4 v[218:219], off
	s_mov_b32 m0, s44
	s_nop 0
	global_load_lds_dwordx4 v[220:221], off
	ds_read_b128 v[182:185], v149 offset:16384
	ds_read_b128 v[186:189], v149 offset:17408
	ds_read_b128 v[190:193], v149 offset:18432
	ds_read_b128 v[194:197], v149 offset:19456
	ds_read_b128 v[198:201], v149 offset:20480
	ds_read_b128 v[202:205], v149 offset:21504
	ds_read_b128 v[206:209], v149 offset:22528
	ds_read_b128 v[210:213], v149 offset:23552
	s_waitcnt vmcnt(8)
	s_waitcnt lgkmcnt(0)
	s_barrier
	s_waitcnt lgkmcnt(0)
	v_mfma_f32_16x16x32_bf16 v[60:63], v[150:153], v[182:185], v[60:63]
	v_mfma_f32_16x16x32_bf16 v[56:59], v[158:161], v[182:185], v[56:59]
	v_mfma_f32_16x16x32_bf16 v[44:47], v[150:153], v[190:193], v[44:47]
	v_mfma_f32_16x16x32_bf16 v[40:43], v[158:161], v[190:193], v[40:43]
	v_mfma_f32_16x16x32_bf16 v[28:31], v[150:153], v[198:201], v[28:31]
	v_mfma_f32_16x16x32_bf16 v[24:27], v[158:161], v[198:201], v[24:27]
	v_mfma_f32_16x16x32_bf16 v[12:15], v[150:153], v[206:209], v[12:15]
	v_mfma_f32_16x16x32_bf16 v[8:11], v[158:161], v[206:209], v[8:11]
	v_mfma_f32_16x16x32_bf16 v[60:63], v[154:157], v[186:189], v[60:63]
	v_mfma_f32_16x16x32_bf16 v[56:59], v[162:165], v[186:189], v[56:59]
	v_mfma_f32_16x16x32_bf16 v[44:47], v[154:157], v[194:197], v[44:47]
	v_mfma_f32_16x16x32_bf16 v[40:43], v[162:165], v[194:197], v[40:43]
	v_mfma_f32_16x16x32_bf16 v[28:31], v[154:157], v[202:205], v[28:31]
	v_mfma_f32_16x16x32_bf16 v[24:27], v[162:165], v[202:205], v[24:27]
	v_mfma_f32_16x16x32_bf16 v[12:15], v[154:157], v[210:213], v[12:15]
	v_mfma_f32_16x16x32_bf16 v[8:11], v[162:165], v[210:213], v[8:11]
	v_mfma_f32_16x16x32_bf16 v[52:55], v[166:169], v[182:185], v[52:55]
	v_mfma_f32_16x16x32_bf16 v[48:51], v[174:177], v[182:185], v[48:51]
	v_mfma_f32_16x16x32_bf16 v[36:39], v[166:169], v[190:193], v[36:39]
	v_mfma_f32_16x16x32_bf16 v[32:35], v[174:177], v[190:193], v[32:35]
	v_mfma_f32_16x16x32_bf16 v[20:23], v[166:169], v[198:201], v[20:23]
	v_mfma_f32_16x16x32_bf16 v[16:19], v[174:177], v[198:201], v[16:19]
	v_mfma_f32_16x16x32_bf16 v[4:7], v[166:169], v[206:209], v[4:7]
	v_mfma_f32_16x16x32_bf16 v[0:3], v[174:177], v[206:209], v[0:3]
	v_mfma_f32_16x16x32_bf16 v[52:55], v[170:173], v[186:189], v[52:55]
	v_mfma_f32_16x16x32_bf16 v[48:51], v[178:181], v[186:189], v[48:51]
	v_mfma_f32_16x16x32_bf16 v[36:39], v[170:173], v[194:197], v[36:39]
	v_mfma_f32_16x16x32_bf16 v[32:35], v[178:181], v[194:197], v[32:35]
	v_mfma_f32_16x16x32_bf16 v[20:23], v[170:173], v[202:205], v[20:23]
	v_mfma_f32_16x16x32_bf16 v[16:19], v[178:181], v[202:205], v[16:19]
	v_mfma_f32_16x16x32_bf16 v[4:7], v[170:173], v[210:213], v[4:7]
	v_mfma_f32_16x16x32_bf16 v[0:3], v[178:181], v[210:213], v[0:3]
	s_barrier
	s_add_i32 s60, 0, 0x18000
	s_add_i32 s61, 0, 0x1c000
	v_add_u32_e32 v162, s60, v144
	v_add_u32_e32 v178, s61, v144
	ds_read_b128 v[150:153], v162
	ds_read_b128 v[154:157], v162 offset:1024
	ds_read_b128 v[158:161], v162 offset:2048
	ds_read_b128 v[162:165], v162 offset:3072
	ds_read_b128 v[166:169], v178
	ds_read_b128 v[170:173], v178 offset:1024
	ds_read_b128 v[174:177], v178 offset:2048
	ds_read_b128 v[178:181], v178 offset:3072
	s_add_u32 s36, s42, 0x80000
	s_addc_u32 s37, s43, 0
	s_mov_b32 m0, s45
	v_lshl_add_u64 v[182:183], s[36:37], 0, v[128:129]
	global_load_lds_dwordx4 v[182:183], off
	v_lshl_add_u64 v[182:183], s[36:37], 0, v[132:133]
	s_mov_b32 m0, s46
	s_nop 0
	global_load_lds_dwordx4 v[182:183], off
	ds_read_b128 v[182:185], v149 offset:32768
	ds_read_b128 v[186:189], v149 offset:33792
	ds_read_b128 v[190:193], v149 offset:34816
	ds_read_b128 v[194:197], v149 offset:35840
	ds_read_b128 v[198:201], v149 offset:36864
	ds_read_b128 v[202:205], v149 offset:37888
	ds_read_b128 v[206:209], v149 offset:38912
	ds_read_b128 v[210:213], v149 offset:39936
	s_waitcnt vmcnt(8)
	s_waitcnt lgkmcnt(0)
	s_barrier
	s_waitcnt lgkmcnt(0)
	v_mfma_f32_16x16x32_bf16 v[124:127], v[150:153], v[182:185], v[124:127]
	v_mfma_f32_16x16x32_bf16 v[120:123], v[158:161], v[182:185], v[120:123]
	v_mfma_f32_16x16x32_bf16 v[108:111], v[150:153], v[190:193], v[108:111]
	v_mfma_f32_16x16x32_bf16 v[104:107], v[158:161], v[190:193], v[104:107]
	v_mfma_f32_16x16x32_bf16 v[92:95], v[150:153], v[198:201], v[92:95]
	v_mfma_f32_16x16x32_bf16 v[88:91], v[158:161], v[198:201], v[88:91]
	v_mfma_f32_16x16x32_bf16 v[76:79], v[150:153], v[206:209], v[76:79]
	v_mfma_f32_16x16x32_bf16 v[72:75], v[158:161], v[206:209], v[72:75]
	v_mfma_f32_16x16x32_bf16 v[124:127], v[154:157], v[186:189], v[124:127]
	v_mfma_f32_16x16x32_bf16 v[120:123], v[162:165], v[186:189], v[120:123]
	v_mfma_f32_16x16x32_bf16 v[108:111], v[154:157], v[194:197], v[108:111]
	v_mfma_f32_16x16x32_bf16 v[104:107], v[162:165], v[194:197], v[104:107]
	v_mfma_f32_16x16x32_bf16 v[92:95], v[154:157], v[202:205], v[92:95]
	v_mfma_f32_16x16x32_bf16 v[88:91], v[162:165], v[202:205], v[88:91]
	v_mfma_f32_16x16x32_bf16 v[76:79], v[154:157], v[210:213], v[76:79]
	v_mfma_f32_16x16x32_bf16 v[72:75], v[162:165], v[210:213], v[72:75]
	v_mfma_f32_16x16x32_bf16 v[116:119], v[166:169], v[182:185], v[116:119]
	v_mfma_f32_16x16x32_bf16 v[112:115], v[174:177], v[182:185], v[112:115]
	v_mfma_f32_16x16x32_bf16 v[100:103], v[166:169], v[190:193], v[100:103]
	v_mfma_f32_16x16x32_bf16 v[96:99], v[174:177], v[190:193], v[96:99]
	v_mfma_f32_16x16x32_bf16 v[84:87], v[166:169], v[198:201], v[84:87]
	v_mfma_f32_16x16x32_bf16 v[80:83], v[174:177], v[198:201], v[80:83]
	v_mfma_f32_16x16x32_bf16 v[68:71], v[166:169], v[206:209], v[68:71]
	v_mfma_f32_16x16x32_bf16 v[64:67], v[174:177], v[206:209], v[64:67]
	v_mfma_f32_16x16x32_bf16 v[116:119], v[170:173], v[186:189], v[116:119]
	v_mfma_f32_16x16x32_bf16 v[112:115], v[178:181], v[186:189], v[112:115]
	v_mfma_f32_16x16x32_bf16 v[100:103], v[170:173], v[194:197], v[100:103]
	v_mfma_f32_16x16x32_bf16 v[96:99], v[178:181], v[194:197], v[96:99]
	v_mfma_f32_16x16x32_bf16 v[84:87], v[170:173], v[202:205], v[84:87]
	v_mfma_f32_16x16x32_bf16 v[80:83], v[178:181], v[202:205], v[80:83]
	v_mfma_f32_16x16x32_bf16 v[68:71], v[170:173], v[210:213], v[68:71]
	v_mfma_f32_16x16x32_bf16 v[64:67], v[178:181], v[210:213], v[64:67]
	s_barrier
	s_add_i32 s36, s60, s11
	v_lshl_add_u64 v[182:183], v[214:215], 0, s[14:15]
	s_mov_b32 m0, s36
	s_nop 0
	global_load_lds_dwordx4 v[182:183], off
	s_add_i32 m0, s36, 0x2000
	s_add_u32 s36, s40, 0x80080
	v_lshl_add_u64 v[182:183], v[216:217], 0, s[14:15]
	s_addc_u32 s37, s41, 0
	s_add_i32 s40, s61, s11
	global_load_lds_dwordx4 v[182:183], off
	v_lshl_add_u64 v[182:183], s[36:37], 0, v[130:131]
	s_mov_b32 m0, s40
	s_nop 0
	global_load_lds_dwordx4 v[182:183], off
	v_lshl_add_u64 v[182:183], s[36:37], 0, v[134:135]
	s_add_i32 m0, s40, 0x2000
	s_nop 0
	global_load_lds_dwordx4 v[182:183], off
	v_lshl_add_u64 v[182:183], v[218:219], 0, s[14:15]
	s_mov_b32 m0, s49
	s_nop 0
	global_load_lds_dwordx4 v[182:183], off
	v_lshl_add_u64 v[182:183], v[220:221], 0, s[14:15]
	s_mov_b32 m0, s50
	s_nop 0
	global_load_lds_dwordx4 v[182:183], off
	ds_read_b128 v[182:185], v149 offset:49152
	ds_read_b128 v[186:189], v149 offset:50176
	ds_read_b128 v[190:193], v149 offset:51200
	ds_read_b128 v[194:197], v149 offset:52224
	ds_read_b128 v[198:201], v149 offset:53248
	ds_read_b128 v[202:205], v149 offset:54272
	ds_read_b128 v[206:209], v149 offset:55296
	ds_read_b128 v[210:213], v149 offset:56320
	s_waitcnt vmcnt(8)
	s_waitcnt lgkmcnt(0)
	s_barrier
	s_waitcnt lgkmcnt(0)
	v_mfma_f32_16x16x32_bf16 v[60:63], v[150:153], v[182:185], v[60:63]
	v_mfma_f32_16x16x32_bf16 v[56:59], v[158:161], v[182:185], v[56:59]
	v_mfma_f32_16x16x32_bf16 v[44:47], v[150:153], v[190:193], v[44:47]
	v_mfma_f32_16x16x32_bf16 v[40:43], v[158:161], v[190:193], v[40:43]
	v_mfma_f32_16x16x32_bf16 v[28:31], v[150:153], v[198:201], v[28:31]
	v_mfma_f32_16x16x32_bf16 v[24:27], v[158:161], v[198:201], v[24:27]
	v_mfma_f32_16x16x32_bf16 v[12:15], v[150:153], v[206:209], v[12:15]
	v_mfma_f32_16x16x32_bf16 v[8:11], v[158:161], v[206:209], v[8:11]
	v_mfma_f32_16x16x32_bf16 v[60:63], v[154:157], v[186:189], v[60:63]
	v_mfma_f32_16x16x32_bf16 v[56:59], v[162:165], v[186:189], v[56:59]
	v_mfma_f32_16x16x32_bf16 v[44:47], v[154:157], v[194:197], v[44:47]
	v_mfma_f32_16x16x32_bf16 v[40:43], v[162:165], v[194:197], v[40:43]
	v_mfma_f32_16x16x32_bf16 v[28:31], v[154:157], v[202:205], v[28:31]
	v_mfma_f32_16x16x32_bf16 v[24:27], v[162:165], v[202:205], v[24:27]
	v_mfma_f32_16x16x32_bf16 v[12:15], v[154:157], v[210:213], v[12:15]
	v_mfma_f32_16x16x32_bf16 v[8:11], v[162:165], v[210:213], v[8:11]
	v_mfma_f32_16x16x32_bf16 v[52:55], v[166:169], v[182:185], v[52:55]
	v_mfma_f32_16x16x32_bf16 v[48:51], v[174:177], v[182:185], v[48:51]
	v_mfma_f32_16x16x32_bf16 v[36:39], v[166:169], v[190:193], v[36:39]
	v_mfma_f32_16x16x32_bf16 v[32:35], v[174:177], v[190:193], v[32:35]
	v_mfma_f32_16x16x32_bf16 v[20:23], v[166:169], v[198:201], v[20:23]
	v_mfma_f32_16x16x32_bf16 v[16:19], v[174:177], v[198:201], v[16:19]
	v_mfma_f32_16x16x32_bf16 v[4:7], v[166:169], v[206:209], v[4:7]
	v_mfma_f32_16x16x32_bf16 v[0:3], v[174:177], v[206:209], v[0:3]
	v_mfma_f32_16x16x32_bf16 v[52:55], v[170:173], v[186:189], v[52:55]
	v_mfma_f32_16x16x32_bf16 v[48:51], v[178:181], v[186:189], v[48:51]
	v_mfma_f32_16x16x32_bf16 v[36:39], v[170:173], v[194:197], v[36:39]
	v_mfma_f32_16x16x32_bf16 v[32:35], v[178:181], v[194:197], v[32:35]
	v_mfma_f32_16x16x32_bf16 v[20:23], v[170:173], v[202:205], v[20:23]
	v_mfma_f32_16x16x32_bf16 v[16:19], v[178:181], v[202:205], v[16:19]
	v_mfma_f32_16x16x32_bf16 v[4:7], v[170:173], v[210:213], v[4:7]
	v_mfma_f32_16x16x32_bf16 v[0:3], v[178:181], v[210:213], v[0:3]
	s_barrier
	s_add_i32 s59, s59, 2
	s_add_u32 s57, s57, 0x100
	s_addc_u32 s58, s58, 0
	s_cmp_gt_u32 s59, 29
	s_mov_b64 s[36:37], s[38:39]
	s_cbranch_scc0 .LBB0_159
	s_setprio 0
	s_and_b64 vcc, exec, s[6:7]
	s_cbranch_vccz .LBB0_162
	s_barrier

.LBB0_247:
	s_add_u32 s63, s46, 0x100
	v_mov_b32_e32 v0, 0
	s_addc_u32 s64, s47, 0
	s_mov_b32 s65, -2
	s_waitcnt lgkmcnt(0)
	v_mov_b32_e32 v1, v0
	v_mov_b32_e32 v2, v0
	v_mov_b32_e32 v3, v0
	v_mov_b32_e32 v4, v0
	v_mov_b32_e32 v5, v0
	v_mov_b32_e32 v6, v0
	v_mov_b32_e32 v7, v0
	v_mov_b32_e32 v16, v0
	v_mov_b32_e32 v17, v0
	v_mov_b32_e32 v18, v0
	v_mov_b32_e32 v19, v0
	v_mov_b32_e32 v20, v0
	v_mov_b32_e32 v21, v0
	v_mov_b32_e32 v22, v0
	v_mov_b32_e32 v23, v0
	v_mov_b32_e32 v32, v0
	v_mov_b32_e32 v33, v0
	v_mov_b32_e32 v34, v0
	v_mov_b32_e32 v35, v0
	v_mov_b32_e32 v36, v0
	v_mov_b32_e32 v37, v0
	v_mov_b32_e32 v38, v0
	v_mov_b32_e32 v39, v0
	v_mov_b32_e32 v48, v0
	v_mov_b32_e32 v49, v0
	v_mov_b32_e32 v50, v0
	v_mov_b32_e32 v51, v0
	v_mov_b32_e32 v52, v0
	v_mov_b32_e32 v53, v0
	v_mov_b32_e32 v54, v0
	v_mov_b32_e32 v55, v0
	v_mov_b32_e32 v8, v0
	v_mov_b32_e32 v9, v0
	v_mov_b32_e32 v10, v0
	v_mov_b32_e32 v11, v0
	v_mov_b32_e32 v12, v0
	v_mov_b32_e32 v13, v0
	v_mov_b32_e32 v14, v0
	v_mov_b32_e32 v15, v0
	v_mov_b32_e32 v24, v0
	v_mov_b32_e32 v25, v0
	v_mov_b32_e32 v26, v0
	v_mov_b32_e32 v27, v0
	v_mov_b32_e32 v28, v0
	v_mov_b32_e32 v29, v0
	v_mov_b32_e32 v30, v0
	v_mov_b32_e32 v31, v0
	v_mov_b32_e32 v40, v0
	v_mov_b32_e32 v41, v0
	v_mov_b32_e32 v42, v0
	v_mov_b32_e32 v43, v0
	v_mov_b32_e32 v44, v0
	v_mov_b32_e32 v45, v0
	v_mov_b32_e32 v46, v0
	v_mov_b32_e32 v47, v0
	v_mov_b32_e32 v56, v0
	v_mov_b32_e32 v57, v0
	v_mov_b32_e32 v58, v0
	v_mov_b32_e32 v59, v0
	v_mov_b32_e32 v60, v0
	v_mov_b32_e32 v61, v0
	v_mov_b32_e32 v62, v0
	v_mov_b32_e32 v63, v0
	v_mov_b32_e32 v64, v0
	v_mov_b32_e32 v65, v0
	v_mov_b32_e32 v66, v0
	v_mov_b32_e32 v67, v0
	v_mov_b32_e32 v68, v0
	v_mov_b32_e32 v69, v0
	v_mov_b32_e32 v70, v0
	v_mov_b32_e32 v71, v0
	v_mov_b32_e32 v80, v0
	v_mov_b32_e32 v81, v0
	v_mov_b32_e32 v82, v0
	v_mov_b32_e32 v83, v0
	v_mov_b32_e32 v84, v0
	v_mov_b32_e32 v85, v0
	v_mov_b32_e32 v86, v0
	v_mov_b32_e32 v87, v0
	v_mov_b32_e32 v96, v0
	v_mov_b32_e32 v97, v0
	v_mov_b32_e32 v98, v0
	v_mov_b32_e32 v99, v0
	v_mov_b32_e32 v100, v0
	v_mov_b32_e32 v101, v0
	v_mov_b32_e32 v102, v0
	v_mov_b32_e32 v103, v0
	v_mov_b32_e32 v112, v0
	v_mov_b32_e32 v113, v0
	v_mov_b32_e32 v114, v0
	v_mov_b32_e32 v115, v0
	v_mov_b32_e32 v116, v0
	v_mov_b32_e32 v117, v0
	v_mov_b32_e32 v118, v0
	v_mov_b32_e32 v119, v0
	v_mov_b32_e32 v72, v0
	v_mov_b32_e32 v73, v0
	v_mov_b32_e32 v74, v0
	v_mov_b32_e32 v75, v0
	v_mov_b32_e32 v76, v0
	v_mov_b32_e32 v77, v0
	v_mov_b32_e32 v78, v0
	v_mov_b32_e32 v79, v0
	v_mov_b32_e32 v88, v0
	v_mov_b32_e32 v89, v0
	v_mov_b32_e32 v90, v0
	v_mov_b32_e32 v91, v0
	v_mov_b32_e32 v92, v0
	v_mov_b32_e32 v93, v0
	v_mov_b32_e32 v94, v0
	v_mov_b32_e32 v95, v0
	v_mov_b32_e32 v104, v0
	v_mov_b32_e32 v105, v0
	v_mov_b32_e32 v106, v0
	v_mov_b32_e32 v107, v0
	v_mov_b32_e32 v108, v0
	v_mov_b32_e32 v109, v0
	v_mov_b32_e32 v110, v0
	v_mov_b32_e32 v111, v0
	v_mov_b32_e32 v120, v0
	v_mov_b32_e32 v121, v0
	v_mov_b32_e32 v122, v0
	v_mov_b32_e32 v123, v0
	v_mov_b32_e32 v124, v0
	v_mov_b32_e32 v125, v0
	v_mov_b32_e32 v126, v0
	v_mov_b32_e32 v127, v0
	s_cmp_lt_u32 s97, 4
	s_cbranch_scc1 .Lgprio1
	s_setprio 1
.Lgprio1:
.LBB0_248:
	ds_read_b128 v[144:147], v161
	ds_read_b128 v[148:151], v161 offset:1024
	ds_read_b128 v[152:155], v161 offset:2048
	ds_read_b128 v[164:167], v161 offset:3072
	ds_read_b128 v[168:171], v162
	ds_read_b128 v[172:175], v162 offset:1024
	ds_read_b128 v[176:179], v162 offset:2048
	ds_read_b128 v[180:183], v162 offset:3072
	s_add_u32 s6, s8, 0x100
	s_addc_u32 s7, s9, 0
	s_cmpk_eq_i32 s65, 0x54
	s_cselect_b32 s49, s43, s7
	s_cselect_b32 s48, s42, s6
	s_cselect_b32 s47, s45, s64
	s_cselect_b32 s46, s44, s63
	v_lshl_add_u64 v[184:185], s[8:9], 0, v[136:137]
	s_add_i32 m0, s53, 0xc000
	s_nop 0
	global_load_lds_dwordx4 v[184:185], off
	v_lshl_add_u64 v[184:185], s[8:9], 0, v[138:139]
	s_add_i32 m0, s53, 0xe000
	s_nop 0
	global_load_lds_dwordx4 v[184:185], off
	ds_read_b128 v[184:187], v163
	ds_read_b128 v[188:191], v163 offset:1024
	ds_read_b128 v[192:195], v163 offset:2048
	ds_read_b128 v[196:199], v163 offset:3072
	ds_read_b128 v[200:203], v163 offset:4096
	ds_read_b128 v[204:207], v163 offset:5120
	ds_read_b128 v[208:211], v163 offset:6144
	ds_read_b128 v[212:215], v163 offset:7168
	s_waitcnt vmcnt(8)
	s_waitcnt lgkmcnt(0)
	s_barrier
	s_waitcnt lgkmcnt(0)
	v_mfma_f32_16x16x32_bf16 v[124:127], v[144:147], v[184:187], v[124:127]
	v_mfma_f32_16x16x32_bf16 v[120:123], v[152:155], v[184:187], v[120:123]
	v_mfma_f32_16x16x32_bf16 v[108:111], v[144:147], v[192:195], v[108:111]
	v_mfma_f32_16x16x32_bf16 v[104:107], v[152:155], v[192:195], v[104:107]
	v_mfma_f32_16x16x32_bf16 v[92:95], v[144:147], v[200:203], v[92:95]
	v_mfma_f32_16x16x32_bf16 v[88:91], v[152:155], v[200:203], v[88:91]
	v_mfma_f32_16x16x32_bf16 v[76:79], v[144:147], v[208:211], v[76:79]
	v_mfma_f32_16x16x32_bf16 v[72:75], v[152:155], v[208:211], v[72:75]
	v_mfma_f32_16x16x32_bf16 v[124:127], v[148:151], v[188:191], v[124:127]
	v_mfma_f32_16x16x32_bf16 v[120:123], v[164:167], v[188:191], v[120:123]
	v_mfma_f32_16x16x32_bf16 v[108:111], v[148:151], v[196:199], v[108:111]
	v_mfma_f32_16x16x32_bf16 v[104:107], v[164:167], v[196:199], v[104:107]
	v_mfma_f32_16x16x32_bf16 v[92:95], v[148:151], v[204:207], v[92:95]
	v_mfma_f32_16x16x32_bf16 v[88:91], v[164:167], v[204:207], v[88:91]
	v_mfma_f32_16x16x32_bf16 v[76:79], v[148:151], v[212:215], v[76:79]
	v_mfma_f32_16x16x32_bf16 v[72:75], v[164:167], v[212:215], v[72:75]
	v_mfma_f32_16x16x32_bf16 v[116:119], v[168:171], v[184:187], v[116:119]
	v_mfma_f32_16x16x32_bf16 v[112:115], v[176:179], v[184:187], v[112:115]
	v_mfma_f32_16x16x32_bf16 v[100:103], v[168:171], v[192:195], v[100:103]
	v_mfma_f32_16x16x32_bf16 v[96:99], v[176:179], v[192:195], v[96:99]
	v_mfma_f32_16x16x32_bf16 v[84:87], v[168:171], v[200:203], v[84:87]
	v_mfma_f32_16x16x32_bf16 v[80:83], v[176:179], v[200:203], v[80:83]
	v_mfma_f32_16x16x32_bf16 v[68:71], v[168:171], v[208:211], v[68:71]
	v_mfma_f32_16x16x32_bf16 v[64:67], v[176:179], v[208:211], v[64:67]
	v_mfma_f32_16x16x32_bf16 v[116:119], v[172:175], v[188:191], v[116:119]
	v_mfma_f32_16x16x32_bf16 v[112:115], v[180:183], v[188:191], v[112:115]
	v_mfma_f32_16x16x32_bf16 v[100:103], v[172:175], v[196:199], v[100:103]
	v_mfma_f32_16x16x32_bf16 v[96:99], v[180:183], v[196:199], v[96:99]
	v_mfma_f32_16x16x32_bf16 v[84:87], v[172:175], v[204:207], v[84:87]
	v_mfma_f32_16x16x32_bf16 v[80:83], v[180:183], v[204:207], v[80:83]
	v_mfma_f32_16x16x32_bf16 v[68:71], v[172:175], v[212:215], v[68:71]
	v_mfma_f32_16x16x32_bf16 v[64:67], v[180:183], v[212:215], v[64:67]
	s_barrier
	s_add_i32 s8, s58, s21
	v_lshl_add_u64 v[216:217], s[46:47], 0, v[130:131]
	s_mov_b32 m0, s8
	v_lshl_add_u64 v[218:219], s[46:47], 0, v[134:135]
	global_load_lds_dwordx4 v[216:217], off
	s_add_i32 m0, s8, 0x2000
	s_add_u32 s8, s46, 0x160000
	s_addc_u32 s9, s47, 0
	s_add_i32 s66, s59, s21
	global_load_lds_dwordx4 v[218:219], off
	v_lshl_add_u64 v[184:185], s[8:9], 0, v[130:131]
	s_mov_b32 m0, s66
	v_lshl_add_u64 v[220:221], s[48:49], 0, v[128:129]
	global_load_lds_dwordx4 v[184:185], off
	v_lshl_add_u64 v[184:185], s[8:9], 0, v[134:135]
	s_add_i32 m0, s66, 0x2000
	v_lshl_add_u64 v[222:223], s[48:49], 0, v[132:133]
	global_load_lds_dwordx4 v[184:185], off
	s_mov_b32 m0, s53
	s_nop 0
	global_load_lds_dwordx4 v[220:221], off
	s_mov_b32 m0, s54
	s_nop 0
	global_load_lds_dwordx4 v[222:223], off
	ds_read_b128 v[184:187], v163 offset:16384
	ds_read_b128 v[188:191], v163 offset:17408
	ds_read_b128 v[192:195], v163 offset:18432
	ds_read_b128 v[196:199], v163 offset:19456
	ds_read_b128 v[200:203], v163 offset:20480
	ds_read_b128 v[204:207], v163 offset:21504
	ds_read_b128 v[208:211], v163 offset:22528
	ds_read_b128 v[212:215], v163 offset:23552
	s_waitcnt vmcnt(8)
	s_waitcnt lgkmcnt(0)
	s_barrier
	s_waitcnt lgkmcnt(0)
	v_mfma_f32_16x16x32_bf16 v[60:63], v[144:147], v[184:187], v[60:63]
	v_mfma_f32_16x16x32_bf16 v[56:59], v[152:155], v[184:187], v[56:59]
	v_mfma_f32_16x16x32_bf16 v[44:47], v[144:147], v[192:195], v[44:47]
	v_mfma_f32_16x16x32_bf16 v[40:43], v[152:155], v[192:195], v[40:43]
	v_mfma_f32_16x16x32_bf16 v[28:31], v[144:147], v[200:203], v[28:31]
	v_mfma_f32_16x16x32_bf16 v[24:27], v[152:155], v[200:203], v[24:27]
	v_mfma_f32_16x16x32_bf16 v[12:15], v[144:147], v[208:211], v[12:15]
	v_mfma_f32_16x16x32_bf16 v[8:11], v[152:155], v[208:211], v[8:11]
	v_mfma_f32_16x16x32_bf16 v[60:63], v[148:151], v[188:191], v[60:63]
	v_mfma_f32_16x16x32_bf16 v[56:59], v[164:167], v[188:191], v[56:59]
	v_mfma_f32_16x16x32_bf16 v[44:47], v[148:151], v[196:199], v[44:47]
	v_mfma_f32_16x16x32_bf16 v[40:43], v[164:167], v[196:199], v[40:43]
	v_mfma_f32_16x16x32_bf16 v[28:31], v[148:151], v[204:207], v[28:31]
	v_mfma_f32_16x16x32_bf16 v[24:27], v[164:167], v[204:207], v[24:27]
	v_mfma_f32_16x16x32_bf16 v[12:15], v[148:151], v[212:215], v[12:15]
	v_mfma_f32_16x16x32_bf16 v[8:11], v[164:167], v[212:215], v[8:11]
	v_mfma_f32_16x16x32_bf16 v[52:55], v[168:171], v[184:187], v[52:55]
	v_mfma_f32_16x16x32_bf16 v[48:51], v[176:179], v[184:187], v[48:51]
	v_mfma_f32_16x16x32_bf16 v[36:39], v[168:171], v[192:195], v[36:39]
	v_mfma_f32_16x16x32_bf16 v[32:35], v[176:179], v[192:195], v[32:35]
	v_mfma_f32_16x16x32_bf16 v[20:23], v[168:171], v[200:203], v[20:23]
	v_mfma_f32_16x16x32_bf16 v[16:19], v[176:179], v[200:203], v[16:19]
	v_mfma_f32_16x16x32_bf16 v[4:7], v[168:171], v[208:211], v[4:7]
	v_mfma_f32_16x16x32_bf16 v[0:3], v[176:179], v[208:211], v[0:3]
	v_mfma_f32_16x16x32_bf16 v[52:55], v[172:175], v[188:191], v[52:55]
	v_mfma_f32_16x16x32_bf16 v[48:51], v[180:183], v[188:191], v[48:51]
	v_mfma_f32_16x16x32_bf16 v[36:39], v[172:175], v[196:199], v[36:39]
	v_mfma_f32_16x16x32_bf16 v[32:35], v[180:183], v[196:199], v[32:35]
	v_mfma_f32_16x16x32_bf16 v[20:23], v[172:175], v[204:207], v[20:23]
	v_mfma_f32_16x16x32_bf16 v[16:19], v[180:183], v[204:207], v[16:19]
	v_mfma_f32_16x16x32_bf16 v[4:7], v[172:175], v[212:215], v[4:7]
	v_mfma_f32_16x16x32_bf16 v[0:3], v[180:183], v[212:215], v[0:3]
	s_barrier
	s_add_i32 s66, 0, 0x18000
	s_add_i32 s67, 0, 0x1c000
	v_add_u32_e32 v164, s66, v156
	v_add_u32_e32 v180, s67, v156
	ds_read_b128 v[144:147], v164
	ds_read_b128 v[148:151], v164 offset:1024
	ds_read_b128 v[152:155], v164 offset:2048
	ds_read_b128 v[164:167], v164 offset:3072
	ds_read_b128 v[168:171], v180
	ds_read_b128 v[172:175], v180 offset:1024
	ds_read_b128 v[176:179], v180 offset:2048
	ds_read_b128 v[180:183], v180 offset:3072
	s_add_u32 s8, s48, 0x160000
	s_addc_u32 s9, s49, 0
	s_mov_b32 m0, s55
	v_lshl_add_u64 v[184:185], s[8:9], 0, v[128:129]
	global_load_lds_dwordx4 v[184:185], off
	v_lshl_add_u64 v[184:185], s[8:9], 0, v[132:133]
	s_mov_b32 m0, s56
	s_nop 0
	global_load_lds_dwordx4 v[184:185], off
	ds_read_b128 v[184:187], v163 offset:32768
	ds_read_b128 v[188:191], v163 offset:33792
	ds_read_b128 v[192:195], v163 offset:34816
	ds_read_b128 v[196:199], v163 offset:35840
	ds_read_b128 v[200:203], v163 offset:36864
	ds_read_b128 v[204:207], v163 offset:37888
	ds_read_b128 v[208:211], v163 offset:38912
	ds_read_b128 v[212:215], v163 offset:39936
	s_waitcnt vmcnt(8)
	s_waitcnt lgkmcnt(0)
	s_barrier
	s_waitcnt lgkmcnt(0)
	v_mfma_f32_16x16x32_bf16 v[124:127], v[144:147], v[184:187], v[124:127]
	v_mfma_f32_16x16x32_bf16 v[120:123], v[152:155], v[184:187], v[120:123]
	v_mfma_f32_16x16x32_bf16 v[108:111], v[144:147], v[192:195], v[108:111]
	v_mfma_f32_16x16x32_bf16 v[104:107], v[152:155], v[192:195], v[104:107]
	v_mfma_f32_16x16x32_bf16 v[92:95], v[144:147], v[200:203], v[92:95]
	v_mfma_f32_16x16x32_bf16 v[88:91], v[152:155], v[200:203], v[88:91]
	v_mfma_f32_16x16x32_bf16 v[76:79], v[144:147], v[208:211], v[76:79]
	v_mfma_f32_16x16x32_bf16 v[72:75], v[152:155], v[208:211], v[72:75]
	v_mfma_f32_16x16x32_bf16 v[124:127], v[148:151], v[188:191], v[124:127]
	v_mfma_f32_16x16x32_bf16 v[120:123], v[164:167], v[188:191], v[120:123]
	v_mfma_f32_16x16x32_bf16 v[108:111], v[148:151], v[196:199], v[108:111]
	v_mfma_f32_16x16x32_bf16 v[104:107], v[164:167], v[196:199], v[104:107]
	v_mfma_f32_16x16x32_bf16 v[92:95], v[148:151], v[204:207], v[92:95]
	v_mfma_f32_16x16x32_bf16 v[88:91], v[164:167], v[204:207], v[88:91]
	v_mfma_f32_16x16x32_bf16 v[76:79], v[148:151], v[212:215], v[76:79]
	v_mfma_f32_16x16x32_bf16 v[72:75], v[164:167], v[212:215], v[72:75]
	v_mfma_f32_16x16x32_bf16 v[116:119], v[168:171], v[184:187], v[116:119]
	v_mfma_f32_16x16x32_bf16 v[112:115], v[176:179], v[184:187], v[112:115]
	v_mfma_f32_16x16x32_bf16 v[100:103], v[168:171], v[192:195], v[100:103]
	v_mfma_f32_16x16x32_bf16 v[96:99], v[176:179], v[192:195], v[96:99]
	v_mfma_f32_16x16x32_bf16 v[84:87], v[168:171], v[200:203], v[84:87]
	v_mfma_f32_16x16x32_bf16 v[80:83], v[176:179], v[200:203], v[80:83]
	v_mfma_f32_16x16x32_bf16 v[68:71], v[168:171], v[208:211], v[68:71]
	v_mfma_f32_16x16x32_bf16 v[64:67], v[176:179], v[208:211], v[64:67]
	v_mfma_f32_16x16x32_bf16 v[116:119], v[172:175], v[188:191], v[116:119]
	v_mfma_f32_16x16x32_bf16 v[112:115], v[180:183], v[188:191], v[112:115]
	v_mfma_f32_16x16x32_bf16 v[100:103], v[172:175], v[196:199], v[100:103]
	v_mfma_f32_16x16x32_bf16 v[96:99], v[180:183], v[196:199], v[96:99]
	v_mfma_f32_16x16x32_bf16 v[84:87], v[172:175], v[204:207], v[84:87]
	v_mfma_f32_16x16x32_bf16 v[80:83], v[180:183], v[204:207], v[80:83]
	v_mfma_f32_16x16x32_bf16 v[68:71], v[172:175], v[212:215], v[68:71]
	v_mfma_f32_16x16x32_bf16 v[64:67], v[180:183], v[212:215], v[64:67]
	s_barrier
	s_add_i32 s8, s66, s21
	v_lshl_add_u64 v[184:185], v[216:217], 0, s[36:37]
	s_mov_b32 m0, s8
	s_nop 0
	global_load_lds_dwordx4 v[184:185], off
	s_add_i32 m0, s8, 0x2000
	s_add_u32 s8, s46, 0x160080
	v_lshl_add_u64 v[184:185], v[218:219], 0, s[36:37]
	s_addc_u32 s9, s47, 0
	s_add_i32 s46, s67, s21
	global_load_lds_dwordx4 v[184:185], off
	v_lshl_add_u64 v[184:185], s[8:9], 0, v[130:131]
	s_mov_b32 m0, s46
	s_nop 0
	global_load_lds_dwordx4 v[184:185], off
	v_lshl_add_u64 v[184:185], s[8:9], 0, v[134:135]
	s_add_i32 m0, s46, 0x2000
	s_nop 0
	global_load_lds_dwordx4 v[184:185], off
	v_lshl_add_u64 v[184:185], v[220:221], 0, s[36:37]
	s_mov_b32 m0, s26
	s_nop 0
	global_load_lds_dwordx4 v[184:185], off
	v_lshl_add_u64 v[184:185], v[222:223], 0, s[36:37]
	s_mov_b32 m0, s27
	s_nop 0
	global_load_lds_dwordx4 v[184:185], off
	ds_read_b128 v[184:187], v163 offset:49152
	ds_read_b128 v[188:191], v163 offset:50176
	ds_read_b128 v[192:195], v163 offset:51200
	ds_read_b128 v[196:199], v163 offset:52224
	ds_read_b128 v[200:203], v163 offset:53248
	ds_read_b128 v[204:207], v163 offset:54272
	ds_read_b128 v[208:211], v163 offset:55296
	ds_read_b128 v[212:215], v163 offset:56320
	s_waitcnt vmcnt(8)
	s_waitcnt lgkmcnt(0)
	s_barrier
	s_waitcnt lgkmcnt(0)
	v_mfma_f32_16x16x32_bf16 v[60:63], v[144:147], v[184:187], v[60:63]
	v_mfma_f32_16x16x32_bf16 v[56:59], v[152:155], v[184:187], v[56:59]
	v_mfma_f32_16x16x32_bf16 v[44:47], v[144:147], v[192:195], v[44:47]
	v_mfma_f32_16x16x32_bf16 v[40:43], v[152:155], v[192:195], v[40:43]
	v_mfma_f32_16x16x32_bf16 v[28:31], v[144:147], v[200:203], v[28:31]
	v_mfma_f32_16x16x32_bf16 v[24:27], v[152:155], v[200:203], v[24:27]
	v_mfma_f32_16x16x32_bf16 v[12:15], v[144:147], v[208:211], v[12:15]
	v_mfma_f32_16x16x32_bf16 v[8:11], v[152:155], v[208:211], v[8:11]
	v_mfma_f32_16x16x32_bf16 v[60:63], v[148:151], v[188:191], v[60:63]
	v_mfma_f32_16x16x32_bf16 v[56:59], v[164:167], v[188:191], v[56:59]
	v_mfma_f32_16x16x32_bf16 v[44:47], v[148:151], v[196:199], v[44:47]
	v_mfma_f32_16x16x32_bf16 v[40:43], v[164:167], v[196:199], v[40:43]
	v_mfma_f32_16x16x32_bf16 v[28:31], v[148:151], v[204:207], v[28:31]
	v_mfma_f32_16x16x32_bf16 v[24:27], v[164:167], v[204:207], v[24:27]
	v_mfma_f32_16x16x32_bf16 v[12:15], v[148:151], v[212:215], v[12:15]
	v_mfma_f32_16x16x32_bf16 v[8:11], v[164:167], v[212:215], v[8:11]
	v_mfma_f32_16x16x32_bf16 v[52:55], v[168:171], v[184:187], v[52:55]
	v_mfma_f32_16x16x32_bf16 v[48:51], v[176:179], v[184:187], v[48:51]
	v_mfma_f32_16x16x32_bf16 v[36:39], v[168:171], v[192:195], v[36:39]
	v_mfma_f32_16x16x32_bf16 v[32:35], v[176:179], v[192:195], v[32:35]
	v_mfma_f32_16x16x32_bf16 v[20:23], v[168:171], v[200:203], v[20:23]
	v_mfma_f32_16x16x32_bf16 v[16:19], v[176:179], v[200:203], v[16:19]
	v_mfma_f32_16x16x32_bf16 v[4:7], v[168:171], v[208:211], v[4:7]
	v_mfma_f32_16x16x32_bf16 v[0:3], v[176:179], v[208:211], v[0:3]
	v_mfma_f32_16x16x32_bf16 v[52:55], v[172:175], v[188:191], v[52:55]
	v_mfma_f32_16x16x32_bf16 v[48:51], v[180:183], v[188:191], v[48:51]
	v_mfma_f32_16x16x32_bf16 v[36:39], v[172:175], v[196:199], v[36:39]
	v_mfma_f32_16x16x32_bf16 v[32:35], v[180:183], v[196:199], v[32:35]
	v_mfma_f32_16x16x32_bf16 v[20:23], v[172:175], v[204:207], v[20:23]
	v_mfma_f32_16x16x32_bf16 v[16:19], v[180:183], v[204:207], v[16:19]
	v_mfma_f32_16x16x32_bf16 v[4:7], v[172:175], v[212:215], v[4:7]
	v_mfma_f32_16x16x32_bf16 v[0:3], v[180:183], v[212:215], v[0:3]
	s_barrier
	s_add_i32 s65, s65, 2
	s_add_u32 s63, s63, 0x100
	s_addc_u32 s64, s64, 0
	s_cmpk_gt_u32 s65, 0x55
	s_mov_b64 s[8:9], s[6:7]
	s_cbranch_scc0 .LBB0_248
	s_setprio 0
	s_and_b64 vcc, exec, s[28:29]
	s_cbranch_vccz .LBB0_251
	s_barrier

.LBB0_386:
	s_ashr_i32 s29, s28, 31
	s_lshl_b64 s[30:31], s[28:29], 20
	s_add_u32 s30, s24, s30
	s_addc_u32 s31, s25, s31
	s_and_b64 s[34:35], s[2:3], exec
	s_cselect_b32 s29, s31, s37
	s_cselect_b32 s60, s30, s36
	s_ashr_i32 s19, s18, 31
	s_lshl_b64 s[34:35], s[18:19], 20
	s_add_u32 s34, s26, s34
	s_addc_u32 s35, s27, s35
	s_and_b64 s[40:41], s[2:3], exec
	s_cselect_b32 s19, s35, s39
	s_cselect_b32 s61, s34, s38
	s_add_u32 s62, s38, 0x100
	v_mov_b32_e32 v0, 0
	s_addc_u32 s63, s39, 0
	s_mov_b32 s64, -2
	v_mov_b32_e32 v1, v0
	v_mov_b32_e32 v2, v0
	v_mov_b32_e32 v3, v0
	v_mov_b32_e32 v4, v0
	v_mov_b32_e32 v5, v0
	v_mov_b32_e32 v6, v0
	v_mov_b32_e32 v7, v0
	v_mov_b32_e32 v16, v0
	v_mov_b32_e32 v17, v0
	v_mov_b32_e32 v18, v0
	v_mov_b32_e32 v19, v0
	v_mov_b32_e32 v20, v0
	v_mov_b32_e32 v21, v0
	v_mov_b32_e32 v22, v0
	v_mov_b32_e32 v23, v0
	v_mov_b32_e32 v32, v0
	v_mov_b32_e32 v33, v0
	v_mov_b32_e32 v34, v0
	v_mov_b32_e32 v35, v0
	v_mov_b32_e32 v36, v0
	v_mov_b32_e32 v37, v0
	v_mov_b32_e32 v38, v0
	v_mov_b32_e32 v39, v0
	v_mov_b32_e32 v48, v0
	v_mov_b32_e32 v49, v0
	v_mov_b32_e32 v50, v0
	v_mov_b32_e32 v51, v0
	v_mov_b32_e32 v52, v0
	v_mov_b32_e32 v53, v0
	v_mov_b32_e32 v54, v0
	v_mov_b32_e32 v55, v0
	v_mov_b32_e32 v8, v0
	v_mov_b32_e32 v9, v0
	v_mov_b32_e32 v10, v0
	v_mov_b32_e32 v11, v0
	v_mov_b32_e32 v12, v0
	v_mov_b32_e32 v13, v0
	v_mov_b32_e32 v14, v0
	v_mov_b32_e32 v15, v0
	v_mov_b32_e32 v24, v0
	v_mov_b32_e32 v25, v0
	v_mov_b32_e32 v26, v0
	v_mov_b32_e32 v27, v0
	v_mov_b32_e32 v28, v0
	v_mov_b32_e32 v29, v0
	v_mov_b32_e32 v30, v0
	v_mov_b32_e32 v31, v0
	v_mov_b32_e32 v40, v0
	v_mov_b32_e32 v41, v0
	v_mov_b32_e32 v42, v0
	v_mov_b32_e32 v43, v0
	v_mov_b32_e32 v44, v0
	v_mov_b32_e32 v45, v0
	v_mov_b32_e32 v46, v0
	v_mov_b32_e32 v47, v0
	v_mov_b32_e32 v56, v0
	v_mov_b32_e32 v57, v0
	v_mov_b32_e32 v58, v0
	v_mov_b32_e32 v59, v0
	v_mov_b32_e32 v60, v0
	v_mov_b32_e32 v61, v0
	v_mov_b32_e32 v62, v0
	v_mov_b32_e32 v63, v0
	v_mov_b32_e32 v64, v0
	v_mov_b32_e32 v65, v0
	v_mov_b32_e32 v66, v0
	v_mov_b32_e32 v67, v0
	v_mov_b32_e32 v68, v0
	v_mov_b32_e32 v69, v0
	v_mov_b32_e32 v70, v0
	v_mov_b32_e32 v71, v0
	v_mov_b32_e32 v80, v0
	v_mov_b32_e32 v81, v0
	v_mov_b32_e32 v82, v0
	v_mov_b32_e32 v83, v0
	v_mov_b32_e32 v84, v0
	v_mov_b32_e32 v85, v0
	v_mov_b32_e32 v86, v0
	v_mov_b32_e32 v87, v0
	v_mov_b32_e32 v96, v0
	v_mov_b32_e32 v97, v0
	v_mov_b32_e32 v98, v0
	v_mov_b32_e32 v99, v0
	v_mov_b32_e32 v100, v0
	v_mov_b32_e32 v101, v0
	v_mov_b32_e32 v102, v0
	v_mov_b32_e32 v103, v0
	v_mov_b32_e32 v112, v0
	v_mov_b32_e32 v113, v0
	v_mov_b32_e32 v114, v0
	v_mov_b32_e32 v115, v0
	v_mov_b32_e32 v116, v0
	v_mov_b32_e32 v117, v0
	v_mov_b32_e32 v118, v0
	v_mov_b32_e32 v119, v0
	v_mov_b32_e32 v72, v0
	v_mov_b32_e32 v73, v0
	v_mov_b32_e32 v74, v0
	v_mov_b32_e32 v75, v0
	v_mov_b32_e32 v76, v0
	v_mov_b32_e32 v77, v0
	v_mov_b32_e32 v78, v0
	v_mov_b32_e32 v79, v0
	v_mov_b32_e32 v88, v0
	v_mov_b32_e32 v89, v0
	v_mov_b32_e32 v90, v0
	v_mov_b32_e32 v91, v0
	v_mov_b32_e32 v92, v0
	v_mov_b32_e32 v93, v0
	v_mov_b32_e32 v94, v0
	v_mov_b32_e32 v95, v0
	v_mov_b32_e32 v104, v0
	v_mov_b32_e32 v105, v0
	v_mov_b32_e32 v106, v0
	v_mov_b32_e32 v107, v0
	v_mov_b32_e32 v108, v0
	v_mov_b32_e32 v109, v0
	v_mov_b32_e32 v110, v0
	v_mov_b32_e32 v111, v0
	v_mov_b32_e32 v120, v0
	v_mov_b32_e32 v121, v0
	v_mov_b32_e32 v122, v0
	v_mov_b32_e32 v123, v0
	v_mov_b32_e32 v124, v0
	v_mov_b32_e32 v125, v0
	v_mov_b32_e32 v126, v0
	v_mov_b32_e32 v127, v0
	s_cmp_lt_u32 s97, 4
	s_cbranch_scc1 .Lgprio2
	s_setprio 1
.Lgprio2:
.LBB0_387:
	ds_read_b128 v[146:149], v156
	ds_read_b128 v[160:163], v156 offset:1024
	ds_read_b128 v[164:167], v156 offset:2048
	ds_read_b128 v[168:171], v156 offset:3072
	ds_read_b128 v[172:175], v157
	ds_read_b128 v[176:179], v157 offset:1024
	ds_read_b128 v[180:183], v157 offset:2048
	ds_read_b128 v[184:187], v157 offset:3072
	s_add_u32 s38, s36, 0x100
	s_addc_u32 s39, s37, 0
	s_cmp_eq_u32 s64, 28
	s_cselect_b32 s43, s29, s39
	s_cselect_b32 s42, s60, s38
	s_cselect_b32 s41, s19, s63
	s_cselect_b32 s40, s61, s62
	v_lshl_add_u64 v[150:151], s[36:37], 0, v[138:139]
	s_add_i32 m0, s46, 0xc000
	s_nop 0
	global_load_lds_dwordx4 v[150:151], off
	v_lshl_add_u64 v[150:151], s[36:37], 0, v[140:141]
	s_add_i32 m0, s46, 0xe000
	s_nop 0
	global_load_lds_dwordx4 v[150:151], off
	ds_read_b128 v[188:191], v158
	ds_read_b128 v[192:195], v158 offset:1024
	ds_read_b128 v[196:199], v158 offset:2048
	ds_read_b128 v[200:203], v158 offset:3072
	ds_read_b128 v[204:207], v158 offset:4096
	ds_read_b128 v[208:211], v158 offset:5120
	ds_read_b128 v[212:215], v158 offset:6144
	ds_read_b128 v[216:219], v158 offset:7168
	s_waitcnt vmcnt(8)
	s_waitcnt lgkmcnt(0)
	s_barrier
	s_waitcnt lgkmcnt(0)
	v_mfma_f32_16x16x32_bf16 v[124:127], v[146:149], v[188:191], v[124:127]
	v_mfma_f32_16x16x32_bf16 v[120:123], v[164:167], v[188:191], v[120:123]
	v_mfma_f32_16x16x32_bf16 v[108:111], v[146:149], v[196:199], v[108:111]
	v_mfma_f32_16x16x32_bf16 v[104:107], v[164:167], v[196:199], v[104:107]
	v_mfma_f32_16x16x32_bf16 v[92:95], v[146:149], v[204:207], v[92:95]
	v_mfma_f32_16x16x32_bf16 v[88:91], v[164:167], v[204:207], v[88:91]
	v_mfma_f32_16x16x32_bf16 v[76:79], v[146:149], v[212:215], v[76:79]
	v_mfma_f32_16x16x32_bf16 v[72:75], v[164:167], v[212:215], v[72:75]
	v_mfma_f32_16x16x32_bf16 v[124:127], v[160:163], v[192:195], v[124:127]
	v_mfma_f32_16x16x32_bf16 v[120:123], v[168:171], v[192:195], v[120:123]
	v_mfma_f32_16x16x32_bf16 v[108:111], v[160:163], v[200:203], v[108:111]
	v_mfma_f32_16x16x32_bf16 v[104:107], v[168:171], v[200:203], v[104:107]
	v_mfma_f32_16x16x32_bf16 v[92:95], v[160:163], v[208:211], v[92:95]
	v_mfma_f32_16x16x32_bf16 v[88:91], v[168:171], v[208:211], v[88:91]
	v_mfma_f32_16x16x32_bf16 v[76:79], v[160:163], v[216:219], v[76:79]
	v_mfma_f32_16x16x32_bf16 v[72:75], v[168:171], v[216:219], v[72:75]
	v_mfma_f32_16x16x32_bf16 v[116:119], v[172:175], v[188:191], v[116:119]
	v_mfma_f32_16x16x32_bf16 v[112:115], v[180:183], v[188:191], v[112:115]
	v_mfma_f32_16x16x32_bf16 v[100:103], v[172:175], v[196:199], v[100:103]
	v_mfma_f32_16x16x32_bf16 v[96:99], v[180:183], v[196:199], v[96:99]
	v_mfma_f32_16x16x32_bf16 v[84:87], v[172:175], v[204:207], v[84:87]
	v_mfma_f32_16x16x32_bf16 v[80:83], v[180:183], v[204:207], v[80:83]
	v_mfma_f32_16x16x32_bf16 v[68:71], v[172:175], v[212:215], v[68:71]
	v_mfma_f32_16x16x32_bf16 v[64:67], v[180:183], v[212:215], v[64:67]
	v_mfma_f32_16x16x32_bf16 v[116:119], v[176:179], v[192:195], v[116:119]
	v_mfma_f32_16x16x32_bf16 v[112:115], v[184:187], v[192:195], v[112:115]
	v_mfma_f32_16x16x32_bf16 v[100:103], v[176:179], v[200:203], v[100:103]
	v_mfma_f32_16x16x32_bf16 v[96:99], v[184:187], v[200:203], v[96:99]
	v_mfma_f32_16x16x32_bf16 v[84:87], v[176:179], v[208:211], v[84:87]
	v_mfma_f32_16x16x32_bf16 v[80:83], v[184:187], v[208:211], v[80:83]
	v_mfma_f32_16x16x32_bf16 v[68:71], v[176:179], v[216:219], v[68:71]
	v_mfma_f32_16x16x32_bf16 v[64:67], v[184:187], v[216:219], v[64:67]
	s_barrier
	s_add_i32 s36, s55, s11
	v_lshl_add_u64 v[150:151], s[40:41], 0, v[130:131]
	s_mov_b32 m0, s36
	v_lshl_add_u64 v[220:221], s[40:41], 0, v[134:135]
	global_load_lds_dwordx4 v[150:151], off
	s_add_i32 m0, s36, 0x2000
	s_add_u32 s36, s40, 0x80000
	s_addc_u32 s37, s41, 0
	s_add_i32 s65, s56, s11
	global_load_lds_dwordx4 v[220:221], off
	v_lshl_add_u64 v[188:189], s[36:37], 0, v[130:131]
	s_mov_b32 m0, s65
	v_lshl_add_u64 v[222:223], s[42:43], 0, v[128:129]
	global_load_lds_dwordx4 v[188:189], off
	v_lshl_add_u64 v[188:189], s[36:37], 0, v[134:135]
	s_add_i32 m0, s65, 0x2000
	v_lshl_add_u64 v[224:225], s[42:43], 0, v[132:133]
	global_load_lds_dwordx4 v[188:189], off
	s_mov_b32 m0, s46
	s_nop 0
	global_load_lds_dwordx4 v[222:223], off
	s_mov_b32 m0, s47
	s_nop 0
	global_load_lds_dwordx4 v[224:225], off
	ds_read_b128 v[188:191], v158 offset:16384
	ds_read_b128 v[192:195], v158 offset:17408
	ds_read_b128 v[196:199], v158 offset:18432
	ds_read_b128 v[200:203], v158 offset:19456
	ds_read_b128 v[204:207], v158 offset:20480
	ds_read_b128 v[208:211], v158 offset:21504
	ds_read_b128 v[212:215], v158 offset:22528
	ds_read_b128 v[216:219], v158 offset:23552
	s_waitcnt vmcnt(8)
	s_waitcnt lgkmcnt(0)
	s_barrier
	s_waitcnt lgkmcnt(0)
	v_mfma_f32_16x16x32_bf16 v[60:63], v[146:149], v[188:191], v[60:63]
	v_mfma_f32_16x16x32_bf16 v[56:59], v[164:167], v[188:191], v[56:59]
	v_mfma_f32_16x16x32_bf16 v[44:47], v[146:149], v[196:199], v[44:47]
	v_mfma_f32_16x16x32_bf16 v[40:43], v[164:167], v[196:199], v[40:43]
	v_mfma_f32_16x16x32_bf16 v[28:31], v[146:149], v[204:207], v[28:31]
	v_mfma_f32_16x16x32_bf16 v[24:27], v[164:167], v[204:207], v[24:27]
	v_mfma_f32_16x16x32_bf16 v[12:15], v[146:149], v[212:215], v[12:15]
	v_mfma_f32_16x16x32_bf16 v[8:11], v[164:167], v[212:215], v[8:11]
	v_mfma_f32_16x16x32_bf16 v[60:63], v[160:163], v[192:195], v[60:63]
	v_mfma_f32_16x16x32_bf16 v[56:59], v[168:171], v[192:195], v[56:59]
	v_mfma_f32_16x16x32_bf16 v[44:47], v[160:163], v[200:203], v[44:47]
	v_mfma_f32_16x16x32_bf16 v[40:43], v[168:171], v[200:203], v[40:43]
	v_mfma_f32_16x16x32_bf16 v[28:31], v[160:163], v[208:211], v[28:31]
	v_mfma_f32_16x16x32_bf16 v[24:27], v[168:171], v[208:211], v[24:27]
	v_mfma_f32_16x16x32_bf16 v[12:15], v[160:163], v[216:219], v[12:15]
	v_mfma_f32_16x16x32_bf16 v[8:11], v[168:171], v[216:219], v[8:11]
	v_mfma_f32_16x16x32_bf16 v[52:55], v[172:175], v[188:191], v[52:55]
	v_mfma_f32_16x16x32_bf16 v[48:51], v[180:183], v[188:191], v[48:51]
	v_mfma_f32_16x16x32_bf16 v[36:39], v[172:175], v[196:199], v[36:39]
	v_mfma_f32_16x16x32_bf16 v[32:35], v[180:183], v[196:199], v[32:35]
	v_mfma_f32_16x16x32_bf16 v[20:23], v[172:175], v[204:207], v[20:23]
	v_mfma_f32_16x16x32_bf16 v[16:19], v[180:183], v[204:207], v[16:19]
	v_mfma_f32_16x16x32_bf16 v[4:7], v[172:175], v[212:215], v[4:7]
	v_mfma_f32_16x16x32_bf16 v[0:3], v[180:183], v[212:215], v[0:3]
	v_mfma_f32_16x16x32_bf16 v[52:55], v[176:179], v[192:195], v[52:55]
	v_mfma_f32_16x16x32_bf16 v[48:51], v[184:187], v[192:195], v[48:51]
	v_mfma_f32_16x16x32_bf16 v[36:39], v[176:179], v[200:203], v[36:39]
	v_mfma_f32_16x16x32_bf16 v[32:35], v[184:187], v[200:203], v[32:35]
	v_mfma_f32_16x16x32_bf16 v[20:23], v[176:179], v[208:211], v[20:23]
	v_mfma_f32_16x16x32_bf16 v[16:19], v[184:187], v[208:211], v[16:19]
	v_mfma_f32_16x16x32_bf16 v[4:7], v[176:179], v[216:219], v[4:7]
	v_mfma_f32_16x16x32_bf16 v[0:3], v[184:187], v[216:219], v[0:3]
	s_barrier
	s_add_i32 s65, 0, 0x18000
	s_add_i32 s66, 0, 0x1c000
	v_add_u32_e32 v168, s65, v154
	v_add_u32_e32 v184, s66, v154
	ds_read_b128 v[146:149], v168
	ds_read_b128 v[160:163], v168 offset:1024
	ds_read_b128 v[164:167], v168 offset:2048
	ds_read_b128 v[168:171], v168 offset:3072
	ds_read_b128 v[172:175], v184
	ds_read_b128 v[176:179], v184 offset:1024
	ds_read_b128 v[180:183], v184 offset:2048
	ds_read_b128 v[184:187], v184 offset:3072
	s_add_u32 s36, s42, 0x80000
	s_addc_u32 s37, s43, 0
	s_mov_b32 m0, s48
	v_lshl_add_u64 v[188:189], s[36:37], 0, v[128:129]
	global_load_lds_dwordx4 v[188:189], off
	v_lshl_add_u64 v[188:189], s[36:37], 0, v[132:133]
	s_mov_b32 m0, s49
	s_nop 0
	global_load_lds_dwordx4 v[188:189], off
	ds_read_b128 v[188:191], v158 offset:32768
	ds_read_b128 v[192:195], v158 offset:33792
	ds_read_b128 v[196:199], v158 offset:34816
	ds_read_b128 v[200:203], v158 offset:35840
	ds_read_b128 v[204:207], v158 offset:36864
	ds_read_b128 v[208:211], v158 offset:37888
	ds_read_b128 v[212:215], v158 offset:38912
	ds_read_b128 v[216:219], v158 offset:39936
	s_waitcnt vmcnt(8)
	s_waitcnt lgkmcnt(0)
	s_barrier
	s_waitcnt lgkmcnt(0)
	v_mfma_f32_16x16x32_bf16 v[124:127], v[146:149], v[188:191], v[124:127]
	v_mfma_f32_16x16x32_bf16 v[120:123], v[164:167], v[188:191], v[120:123]
	v_mfma_f32_16x16x32_bf16 v[108:111], v[146:149], v[196:199], v[108:111]
	v_mfma_f32_16x16x32_bf16 v[104:107], v[164:167], v[196:199], v[104:107]
	v_mfma_f32_16x16x32_bf16 v[92:95], v[146:149], v[204:207], v[92:95]
	v_mfma_f32_16x16x32_bf16 v[88:91], v[164:167], v[204:207], v[88:91]
	v_mfma_f32_16x16x32_bf16 v[76:79], v[146:149], v[212:215], v[76:79]
	v_mfma_f32_16x16x32_bf16 v[72:75], v[164:167], v[212:215], v[72:75]
	v_mfma_f32_16x16x32_bf16 v[124:127], v[160:163], v[192:195], v[124:127]
	v_mfma_f32_16x16x32_bf16 v[120:123], v[168:171], v[192:195], v[120:123]
	v_mfma_f32_16x16x32_bf16 v[108:111], v[160:163], v[200:203], v[108:111]
	v_mfma_f32_16x16x32_bf16 v[104:107], v[168:171], v[200:203], v[104:107]
	v_mfma_f32_16x16x32_bf16 v[92:95], v[160:163], v[208:211], v[92:95]
	v_mfma_f32_16x16x32_bf16 v[88:91], v[168:171], v[208:211], v[88:91]
	v_mfma_f32_16x16x32_bf16 v[76:79], v[160:163], v[216:219], v[76:79]
	v_mfma_f32_16x16x32_bf16 v[72:75], v[168:171], v[216:219], v[72:75]
	v_mfma_f32_16x16x32_bf16 v[116:119], v[172:175], v[188:191], v[116:119]
	v_mfma_f32_16x16x32_bf16 v[112:115], v[180:183], v[188:191], v[112:115]
	v_mfma_f32_16x16x32_bf16 v[100:103], v[172:175], v[196:199], v[100:103]
	v_mfma_f32_16x16x32_bf16 v[96:99], v[180:183], v[196:199], v[96:99]
	v_mfma_f32_16x16x32_bf16 v[84:87], v[172:175], v[204:207], v[84:87]
	v_mfma_f32_16x16x32_bf16 v[80:83], v[180:183], v[204:207], v[80:83]
	v_mfma_f32_16x16x32_bf16 v[68:71], v[172:175], v[212:215], v[68:71]
	v_mfma_f32_16x16x32_bf16 v[64:67], v[180:183], v[212:215], v[64:67]
	v_mfma_f32_16x16x32_bf16 v[116:119], v[176:179], v[192:195], v[116:119]
	v_mfma_f32_16x16x32_bf16 v[112:115], v[184:187], v[192:195], v[112:115]
	v_mfma_f32_16x16x32_bf16 v[100:103], v[176:179], v[200:203], v[100:103]
	v_mfma_f32_16x16x32_bf16 v[96:99], v[184:187], v[200:203], v[96:99]
	v_mfma_f32_16x16x32_bf16 v[84:87], v[176:179], v[208:211], v[84:87]
	v_mfma_f32_16x16x32_bf16 v[80:83], v[184:187], v[208:211], v[80:83]
	v_mfma_f32_16x16x32_bf16 v[68:71], v[176:179], v[216:219], v[68:71]
	v_mfma_f32_16x16x32_bf16 v[64:67], v[184:187], v[216:219], v[64:67]
	s_barrier
	s_add_i32 s36, s65, s11
	v_lshl_add_u64 v[150:151], v[150:151], 0, s[14:15]
	s_mov_b32 m0, s36
	s_nop 0
	global_load_lds_dwordx4 v[150:151], off
	s_add_i32 m0, s36, 0x2000
	s_add_u32 s36, s40, 0x80080
	v_lshl_add_u64 v[150:151], v[220:221], 0, s[14:15]
	s_addc_u32 s37, s41, 0
	s_add_i32 s40, s66, s11
	global_load_lds_dwordx4 v[150:151], off
	v_lshl_add_u64 v[150:151], s[36:37], 0, v[130:131]
	s_mov_b32 m0, s40
	s_nop 0
	global_load_lds_dwordx4 v[150:151], off
	v_lshl_add_u64 v[150:151], s[36:37], 0, v[134:135]
	s_add_i32 m0, s40, 0x2000
	s_nop 0
	global_load_lds_dwordx4 v[150:151], off
	v_lshl_add_u64 v[150:151], v[222:223], 0, s[14:15]
	s_mov_b32 m0, s53
	s_nop 0
	global_load_lds_dwordx4 v[150:151], off
	v_lshl_add_u64 v[150:151], v[224:225], 0, s[14:15]
	s_mov_b32 m0, s54
	s_nop 0
	global_load_lds_dwordx4 v[150:151], off
	ds_read_b128 v[188:191], v158 offset:49152
	ds_read_b128 v[192:195], v158 offset:50176
	ds_read_b128 v[196:199], v158 offset:51200
	ds_read_b128 v[200:203], v158 offset:52224
	ds_read_b128 v[204:207], v158 offset:53248
	ds_read_b128 v[208:211], v158 offset:54272
	ds_read_b128 v[212:215], v158 offset:55296
	ds_read_b128 v[216:219], v158 offset:56320
	s_waitcnt vmcnt(8)
	s_waitcnt lgkmcnt(0)
	s_barrier
	s_waitcnt lgkmcnt(0)
	v_mfma_f32_16x16x32_bf16 v[60:63], v[146:149], v[188:191], v[60:63]
	v_mfma_f32_16x16x32_bf16 v[56:59], v[164:167], v[188:191], v[56:59]
	v_mfma_f32_16x16x32_bf16 v[44:47], v[146:149], v[196:199], v[44:47]
	v_mfma_f32_16x16x32_bf16 v[40:43], v[164:167], v[196:199], v[40:43]
	v_mfma_f32_16x16x32_bf16 v[28:31], v[146:149], v[204:207], v[28:31]
	v_mfma_f32_16x16x32_bf16 v[24:27], v[164:167], v[204:207], v[24:27]
	v_mfma_f32_16x16x32_bf16 v[12:15], v[146:149], v[212:215], v[12:15]
	v_mfma_f32_16x16x32_bf16 v[8:11], v[164:167], v[212:215], v[8:11]
	v_mfma_f32_16x16x32_bf16 v[60:63], v[160:163], v[192:195], v[60:63]
	v_mfma_f32_16x16x32_bf16 v[56:59], v[168:171], v[192:195], v[56:59]
	v_mfma_f32_16x16x32_bf16 v[44:47], v[160:163], v[200:203], v[44:47]
	v_mfma_f32_16x16x32_bf16 v[40:43], v[168:171], v[200:203], v[40:43]
	v_mfma_f32_16x16x32_bf16 v[28:31], v[160:163], v[208:211], v[28:31]
	v_mfma_f32_16x16x32_bf16 v[24:27], v[168:171], v[208:211], v[24:27]
	v_mfma_f32_16x16x32_bf16 v[12:15], v[160:163], v[216:219], v[12:15]
	v_mfma_f32_16x16x32_bf16 v[8:11], v[168:171], v[216:219], v[8:11]
	v_mfma_f32_16x16x32_bf16 v[52:55], v[172:175], v[188:191], v[52:55]
	v_mfma_f32_16x16x32_bf16 v[48:51], v[180:183], v[188:191], v[48:51]
	v_mfma_f32_16x16x32_bf16 v[36:39], v[172:175], v[196:199], v[36:39]
	v_mfma_f32_16x16x32_bf16 v[32:35], v[180:183], v[196:199], v[32:35]
	v_mfma_f32_16x16x32_bf16 v[20:23], v[172:175], v[204:207], v[20:23]
	v_mfma_f32_16x16x32_bf16 v[16:19], v[180:183], v[204:207], v[16:19]
	v_mfma_f32_16x16x32_bf16 v[4:7], v[172:175], v[212:215], v[4:7]
	v_mfma_f32_16x16x32_bf16 v[0:3], v[180:183], v[212:215], v[0:3]
	v_mfma_f32_16x16x32_bf16 v[52:55], v[176:179], v[192:195], v[52:55]
	v_mfma_f32_16x16x32_bf16 v[48:51], v[184:187], v[192:195], v[48:51]
	v_mfma_f32_16x16x32_bf16 v[36:39], v[176:179], v[200:203], v[36:39]
	v_mfma_f32_16x16x32_bf16 v[32:35], v[184:187], v[200:203], v[32:35]
	v_mfma_f32_16x16x32_bf16 v[20:23], v[176:179], v[208:211], v[20:23]
	v_mfma_f32_16x16x32_bf16 v[16:19], v[184:187], v[208:211], v[16:19]
	v_mfma_f32_16x16x32_bf16 v[4:7], v[176:179], v[216:219], v[4:7]
	v_mfma_f32_16x16x32_bf16 v[0:3], v[184:187], v[216:219], v[0:3]
	s_barrier
	s_add_i32 s64, s64, 2
	s_add_u32 s62, s62, 0x100
	s_addc_u32 s63, s63, 0
	s_cmp_gt_u32 s64, 29
	s_mov_b64 s[36:37], s[38:39]
	s_cbranch_scc0 .LBB0_387
	s_setprio 0
	s_and_b64 vcc, exec, s[4:5]
	s_cbranch_vccnz .LBB0_392
	s_cmp_gt_i32 s59, 11
	s_mov_b64 s[36:37], -1
	s_cbranch_scc1 .LBB0_393

.LBB0_1116:
	s_ashr_i32 s39, s38, 31
	s_lshl_b64 s[40:41], s[38:39], 20
	s_add_u32 s40, s23, s40
	s_addc_u32 s41, s52, s41
	s_and_b64 s[42:43], s[4:5], exec
	s_cselect_b32 s7, s41, s47
	s_cselect_b32 s11, s40, s46
	s_ashr_i32 s37, s36, 31
	s_lshl_b64 s[42:43], s[36:37], 20
	s_add_u32 s42, s53, s42
	s_addc_u32 s43, s54, s43
	s_and_b64 s[50:51], s[4:5], exec
	s_cselect_b32 s37, s43, s49
	s_cselect_b32 s39, s42, s48
	s_add_u32 s46, s46, 0x80080
	s_addc_u32 s47, s47, 0
	s_add_u32 s45, s48, 0x100
	v_mov_b32_e32 v0, 0
	s_addc_u32 s62, s49, 0
	s_mov_b32 s63, -2
	v_mov_b32_e32 v1, v0
	v_mov_b32_e32 v2, v0
	v_mov_b32_e32 v3, v0
	v_mov_b32_e32 v4, v0
	s_waitcnt lgkmcnt(0)
	v_mov_b32_e32 v5, v0
	v_mov_b32_e32 v6, v0
	v_mov_b32_e32 v7, v0
	v_mov_b32_e32 v16, v0
	v_mov_b32_e32 v17, v0
	v_mov_b32_e32 v18, v0
	v_mov_b32_e32 v19, v0
	v_mov_b32_e32 v20, v0
	v_mov_b32_e32 v21, v0
	v_mov_b32_e32 v22, v0
	v_mov_b32_e32 v23, v0
	v_mov_b32_e32 v32, v0
	v_mov_b32_e32 v33, v0
	v_mov_b32_e32 v34, v0
	v_mov_b32_e32 v35, v0
	v_mov_b32_e32 v36, v0
	v_mov_b32_e32 v37, v0
	v_mov_b32_e32 v38, v0
	v_mov_b32_e32 v39, v0
	v_mov_b32_e32 v48, v0
	v_mov_b32_e32 v49, v0
	v_mov_b32_e32 v50, v0
	v_mov_b32_e32 v51, v0
	v_mov_b32_e32 v52, v0
	v_mov_b32_e32 v53, v0
	v_mov_b32_e32 v54, v0
	v_mov_b32_e32 v55, v0
	v_mov_b32_e32 v8, v0
	v_mov_b32_e32 v9, v0
	v_mov_b32_e32 v10, v0
	v_mov_b32_e32 v11, v0
	v_mov_b32_e32 v12, v0
	v_mov_b32_e32 v13, v0
	v_mov_b32_e32 v14, v0
	v_mov_b32_e32 v15, v0
	v_mov_b32_e32 v24, v0
	v_mov_b32_e32 v25, v0
	v_mov_b32_e32 v26, v0
	v_mov_b32_e32 v27, v0
	v_mov_b32_e32 v28, v0
	v_mov_b32_e32 v29, v0
	v_mov_b32_e32 v30, v0
	v_mov_b32_e32 v31, v0
	v_mov_b32_e32 v40, v0
	v_mov_b32_e32 v41, v0
	v_mov_b32_e32 v42, v0
	v_mov_b32_e32 v43, v0
	v_mov_b32_e32 v44, v0
	v_mov_b32_e32 v45, v0
	v_mov_b32_e32 v46, v0
	v_mov_b32_e32 v47, v0
	v_mov_b32_e32 v56, v0
	v_mov_b32_e32 v57, v0
	v_mov_b32_e32 v58, v0
	v_mov_b32_e32 v59, v0
	v_mov_b32_e32 v60, v0
	v_mov_b32_e32 v61, v0
	v_mov_b32_e32 v62, v0
	v_mov_b32_e32 v63, v0
	v_mov_b32_e32 v64, v0
	v_mov_b32_e32 v65, v0
	v_mov_b32_e32 v66, v0
	v_mov_b32_e32 v67, v0
	v_mov_b32_e32 v68, v0
	v_mov_b32_e32 v69, v0
	v_mov_b32_e32 v70, v0
	v_mov_b32_e32 v71, v0
	v_mov_b32_e32 v80, v0
	v_mov_b32_e32 v81, v0
	v_mov_b32_e32 v82, v0
	v_mov_b32_e32 v83, v0
	v_mov_b32_e32 v84, v0
	v_mov_b32_e32 v85, v0
	v_mov_b32_e32 v86, v0
	v_mov_b32_e32 v87, v0
	v_mov_b32_e32 v96, v0
	v_mov_b32_e32 v97, v0
	v_mov_b32_e32 v98, v0
	v_mov_b32_e32 v99, v0
	v_mov_b32_e32 v100, v0
	v_mov_b32_e32 v101, v0
	v_mov_b32_e32 v102, v0
	v_mov_b32_e32 v103, v0
	v_mov_b32_e32 v112, v0
	v_mov_b32_e32 v113, v0
	v_mov_b32_e32 v114, v0
	v_mov_b32_e32 v115, v0
	v_mov_b32_e32 v116, v0
	v_mov_b32_e32 v117, v0
	v_mov_b32_e32 v118, v0
	v_mov_b32_e32 v119, v0
	v_mov_b32_e32 v72, v0
	v_mov_b32_e32 v73, v0
	v_mov_b32_e32 v74, v0
	v_mov_b32_e32 v75, v0
	v_mov_b32_e32 v76, v0
	v_mov_b32_e32 v77, v0
	v_mov_b32_e32 v78, v0
	v_mov_b32_e32 v79, v0
	v_mov_b32_e32 v88, v0
	v_mov_b32_e32 v89, v0
	v_mov_b32_e32 v90, v0
	v_mov_b32_e32 v91, v0
	v_mov_b32_e32 v92, v0
	v_mov_b32_e32 v93, v0
	v_mov_b32_e32 v94, v0
	v_mov_b32_e32 v95, v0
	v_mov_b32_e32 v104, v0
	v_mov_b32_e32 v105, v0
	v_mov_b32_e32 v106, v0
	v_mov_b32_e32 v107, v0
	v_mov_b32_e32 v108, v0
	v_mov_b32_e32 v109, v0
	v_mov_b32_e32 v110, v0
	v_mov_b32_e32 v111, v0
	v_mov_b32_e32 v120, v0
	v_mov_b32_e32 v121, v0
	v_mov_b32_e32 v122, v0
	v_mov_b32_e32 v123, v0
	v_mov_b32_e32 v124, v0
	v_mov_b32_e32 v125, v0
	v_mov_b32_e32 v126, v0
	v_mov_b32_e32 v127, v0
	s_cmp_lt_u32 s97, 4
	s_cbranch_scc1 .Lgprio3
	s_setprio 1
.Lgprio3:
.LBB0_1117:
	ds_read_b128 v[144:147], v159
	ds_read_b128 v[148:151], v159 offset:1024
	ds_read_b128 v[162:165], v159 offset:2048
	ds_read_b128 v[166:169], v159 offset:3072
	ds_read_b128 v[170:173], v160
	ds_read_b128 v[174:177], v160 offset:1024
	ds_read_b128 v[178:181], v160 offset:2048
	ds_read_b128 v[182:185], v160 offset:3072
	s_add_u32 s48, s46, 0xfff80080
	s_addc_u32 s49, s47, -1
	s_cmp_eq_u32 s63, 28
	s_cselect_b32 s51, s7, s49
	s_cselect_b32 s50, s11, s48
	s_cselect_b32 s49, s37, s62
	s_cselect_b32 s48, s39, s45
	v_lshl_add_u64 v[152:153], s[46:47], 0, v[136:137]
	s_add_i32 m0, s55, 0xc000
	s_nop 0
	global_load_lds_dwordx4 v[152:153], off
	v_lshl_add_u64 v[152:153], s[46:47], 0, v[138:139]
	s_add_i32 m0, s55, 0xe000
	s_nop 0
	global_load_lds_dwordx4 v[152:153], off
	ds_read_b128 v[186:189], v161
	ds_read_b128 v[190:193], v161 offset:1024
	ds_read_b128 v[194:197], v161 offset:2048
	ds_read_b128 v[198:201], v161 offset:3072
	ds_read_b128 v[202:205], v161 offset:4096
	ds_read_b128 v[206:209], v161 offset:5120
	ds_read_b128 v[210:213], v161 offset:6144
	ds_read_b128 v[214:217], v161 offset:7168
	s_waitcnt vmcnt(8)
	s_waitcnt lgkmcnt(0)
	s_barrier
	s_waitcnt lgkmcnt(0)
	v_mfma_f32_16x16x32_bf16 v[124:127], v[144:147], v[186:189], v[124:127]
	v_mfma_f32_16x16x32_bf16 v[120:123], v[162:165], v[186:189], v[120:123]
	v_mfma_f32_16x16x32_bf16 v[108:111], v[144:147], v[194:197], v[108:111]
	v_mfma_f32_16x16x32_bf16 v[104:107], v[162:165], v[194:197], v[104:107]
	v_mfma_f32_16x16x32_bf16 v[92:95], v[144:147], v[202:205], v[92:95]
	v_mfma_f32_16x16x32_bf16 v[88:91], v[162:165], v[202:205], v[88:91]
	v_mfma_f32_16x16x32_bf16 v[76:79], v[144:147], v[210:213], v[76:79]
	v_mfma_f32_16x16x32_bf16 v[72:75], v[162:165], v[210:213], v[72:75]
	v_mfma_f32_16x16x32_bf16 v[124:127], v[148:151], v[190:193], v[124:127]
	v_mfma_f32_16x16x32_bf16 v[120:123], v[166:169], v[190:193], v[120:123]
	v_mfma_f32_16x16x32_bf16 v[108:111], v[148:151], v[198:201], v[108:111]
	v_mfma_f32_16x16x32_bf16 v[104:107], v[166:169], v[198:201], v[104:107]
	v_mfma_f32_16x16x32_bf16 v[92:95], v[148:151], v[206:209], v[92:95]
	v_mfma_f32_16x16x32_bf16 v[88:91], v[166:169], v[206:209], v[88:91]
	v_mfma_f32_16x16x32_bf16 v[76:79], v[148:151], v[214:217], v[76:79]
	v_mfma_f32_16x16x32_bf16 v[72:75], v[166:169], v[214:217], v[72:75]
	v_mfma_f32_16x16x32_bf16 v[116:119], v[170:173], v[186:189], v[116:119]
	v_mfma_f32_16x16x32_bf16 v[112:115], v[178:181], v[186:189], v[112:115]
	v_mfma_f32_16x16x32_bf16 v[100:103], v[170:173], v[194:197], v[100:103]
	v_mfma_f32_16x16x32_bf16 v[96:99], v[178:181], v[194:197], v[96:99]
	v_mfma_f32_16x16x32_bf16 v[84:87], v[170:173], v[202:205], v[84:87]
	v_mfma_f32_16x16x32_bf16 v[80:83], v[178:181], v[202:205], v[80:83]
	v_mfma_f32_16x16x32_bf16 v[68:71], v[170:173], v[210:213], v[68:71]
	v_mfma_f32_16x16x32_bf16 v[64:67], v[178:181], v[210:213], v[64:67]
	v_mfma_f32_16x16x32_bf16 v[116:119], v[174:177], v[190:193], v[116:119]
	v_mfma_f32_16x16x32_bf16 v[112:115], v[182:185], v[190:193], v[112:115]
	v_mfma_f32_16x16x32_bf16 v[100:103], v[174:177], v[198:201], v[100:103]
	v_mfma_f32_16x16x32_bf16 v[96:99], v[182:185], v[198:201], v[96:99]
	v_mfma_f32_16x16x32_bf16 v[84:87], v[174:177], v[206:209], v[84:87]
	v_mfma_f32_16x16x32_bf16 v[80:83], v[182:185], v[206:209], v[80:83]
	v_mfma_f32_16x16x32_bf16 v[68:71], v[174:177], v[214:217], v[68:71]
	v_mfma_f32_16x16x32_bf16 v[64:67], v[182:185], v[214:217], v[64:67]
	s_barrier
	s_add_i32 s64, s60, s21
	v_lshl_add_u64 v[152:153], s[48:49], 0, v[130:131]
	s_mov_b32 m0, s64
	v_lshl_add_u64 v[218:219], s[48:49], 0, v[134:135]
	global_load_lds_dwordx4 v[152:153], off
	s_add_i32 m0, s64, 0x2000
	s_add_u32 s64, s48, 0x80000
	s_addc_u32 s65, s49, 0
	s_add_i32 s66, s61, s21
	global_load_lds_dwordx4 v[218:219], off
	v_lshl_add_u64 v[186:187], s[64:65], 0, v[130:131]
	s_mov_b32 m0, s66
	v_lshl_add_u64 v[220:221], s[50:51], 0, v[128:129]
	global_load_lds_dwordx4 v[186:187], off
	v_lshl_add_u64 v[186:187], s[64:65], 0, v[134:135]
	s_add_i32 m0, s66, 0x2000
	v_lshl_add_u64 v[222:223], s[50:51], 0, v[132:133]
	global_load_lds_dwordx4 v[186:187], off
	s_mov_b32 m0, s55
	s_nop 0
	global_load_lds_dwordx4 v[220:221], off
	s_mov_b32 m0, s56
	s_nop 0
	global_load_lds_dwordx4 v[222:223], off
	ds_read_b128 v[186:189], v161 offset:16384
	ds_read_b128 v[190:193], v161 offset:17408
	ds_read_b128 v[194:197], v161 offset:18432
	ds_read_b128 v[198:201], v161 offset:19456
	ds_read_b128 v[202:205], v161 offset:20480
	ds_read_b128 v[206:209], v161 offset:21504
	ds_read_b128 v[210:213], v161 offset:22528
	ds_read_b128 v[214:217], v161 offset:23552
	s_waitcnt vmcnt(8)
	s_waitcnt lgkmcnt(0)
	s_barrier
	s_waitcnt lgkmcnt(0)
	v_mfma_f32_16x16x32_bf16 v[60:63], v[144:147], v[186:189], v[60:63]
	v_mfma_f32_16x16x32_bf16 v[56:59], v[162:165], v[186:189], v[56:59]
	v_mfma_f32_16x16x32_bf16 v[44:47], v[144:147], v[194:197], v[44:47]
	v_mfma_f32_16x16x32_bf16 v[40:43], v[162:165], v[194:197], v[40:43]
	v_mfma_f32_16x16x32_bf16 v[28:31], v[144:147], v[202:205], v[28:31]
	v_mfma_f32_16x16x32_bf16 v[24:27], v[162:165], v[202:205], v[24:27]
	v_mfma_f32_16x16x32_bf16 v[12:15], v[144:147], v[210:213], v[12:15]
	v_mfma_f32_16x16x32_bf16 v[8:11], v[162:165], v[210:213], v[8:11]
	v_mfma_f32_16x16x32_bf16 v[60:63], v[148:151], v[190:193], v[60:63]
	v_mfma_f32_16x16x32_bf16 v[56:59], v[166:169], v[190:193], v[56:59]
	v_mfma_f32_16x16x32_bf16 v[44:47], v[148:151], v[198:201], v[44:47]
	v_mfma_f32_16x16x32_bf16 v[40:43], v[166:169], v[198:201], v[40:43]
	v_mfma_f32_16x16x32_bf16 v[28:31], v[148:151], v[206:209], v[28:31]
	v_mfma_f32_16x16x32_bf16 v[24:27], v[166:169], v[206:209], v[24:27]
	v_mfma_f32_16x16x32_bf16 v[12:15], v[148:151], v[214:217], v[12:15]
	v_mfma_f32_16x16x32_bf16 v[8:11], v[166:169], v[214:217], v[8:11]
	v_mfma_f32_16x16x32_bf16 v[52:55], v[170:173], v[186:189], v[52:55]
	v_mfma_f32_16x16x32_bf16 v[48:51], v[178:181], v[186:189], v[48:51]
	v_mfma_f32_16x16x32_bf16 v[36:39], v[170:173], v[194:197], v[36:39]
	v_mfma_f32_16x16x32_bf16 v[32:35], v[178:181], v[194:197], v[32:35]
	v_mfma_f32_16x16x32_bf16 v[20:23], v[170:173], v[202:205], v[20:23]
	v_mfma_f32_16x16x32_bf16 v[16:19], v[178:181], v[202:205], v[16:19]
	v_mfma_f32_16x16x32_bf16 v[4:7], v[170:173], v[210:213], v[4:7]
	v_mfma_f32_16x16x32_bf16 v[0:3], v[178:181], v[210:213], v[0:3]
	v_mfma_f32_16x16x32_bf16 v[52:55], v[174:177], v[190:193], v[52:55]
	v_mfma_f32_16x16x32_bf16 v[48:51], v[182:185], v[190:193], v[48:51]
	v_mfma_f32_16x16x32_bf16 v[36:39], v[174:177], v[198:201], v[36:39]
	v_mfma_f32_16x16x32_bf16 v[32:35], v[182:185], v[198:201], v[32:35]
	v_mfma_f32_16x16x32_bf16 v[20:23], v[174:177], v[206:209], v[20:23]
	v_mfma_f32_16x16x32_bf16 v[16:19], v[182:185], v[206:209], v[16:19]
	v_mfma_f32_16x16x32_bf16 v[4:7], v[174:177], v[214:217], v[4:7]
	v_mfma_f32_16x16x32_bf16 v[0:3], v[182:185], v[214:217], v[0:3]
	s_barrier
	s_add_i32 s64, 0, 0x18000
	s_add_i32 s65, 0, 0x1c000
	v_add_u32_e32 v166, s64, v154
	v_add_u32_e32 v182, s65, v154
	ds_read_b128 v[144:147], v166
	ds_read_b128 v[148:151], v166 offset:1024
	ds_read_b128 v[162:165], v166 offset:2048
	ds_read_b128 v[166:169], v166 offset:3072
	ds_read_b128 v[170:173], v182
	ds_read_b128 v[174:177], v182 offset:1024
	ds_read_b128 v[178:181], v182 offset:2048
	ds_read_b128 v[182:185], v182 offset:3072
	s_add_u32 s50, s50, 0x80000
	s_addc_u32 s51, s51, 0
	s_mov_b32 m0, s57
	v_lshl_add_u64 v[186:187], s[50:51], 0, v[128:129]
	global_load_lds_dwordx4 v[186:187], off
	v_lshl_add_u64 v[186:187], s[50:51], 0, v[132:133]
	s_mov_b32 m0, s58
	s_nop 0
	global_load_lds_dwordx4 v[186:187], off
	ds_read_b128 v[186:189], v161 offset:32768
	ds_read_b128 v[190:193], v161 offset:33792
	ds_read_b128 v[194:197], v161 offset:34816
	ds_read_b128 v[198:201], v161 offset:35840
	ds_read_b128 v[202:205], v161 offset:36864
	ds_read_b128 v[206:209], v161 offset:37888
	ds_read_b128 v[210:213], v161 offset:38912
	ds_read_b128 v[214:217], v161 offset:39936
	s_waitcnt vmcnt(8)
	s_waitcnt lgkmcnt(0)
	s_barrier
	s_waitcnt lgkmcnt(0)
	v_mfma_f32_16x16x32_bf16 v[124:127], v[144:147], v[186:189], v[124:127]
	v_mfma_f32_16x16x32_bf16 v[120:123], v[162:165], v[186:189], v[120:123]
	v_mfma_f32_16x16x32_bf16 v[108:111], v[144:147], v[194:197], v[108:111]
	v_mfma_f32_16x16x32_bf16 v[104:107], v[162:165], v[194:197], v[104:107]
	v_mfma_f32_16x16x32_bf16 v[92:95], v[144:147], v[202:205], v[92:95]
	v_mfma_f32_16x16x32_bf16 v[88:91], v[162:165], v[202:205], v[88:91]
	v_mfma_f32_16x16x32_bf16 v[76:79], v[144:147], v[210:213], v[76:79]
	v_mfma_f32_16x16x32_bf16 v[72:75], v[162:165], v[210:213], v[72:75]
	v_mfma_f32_16x16x32_bf16 v[124:127], v[148:151], v[190:193], v[124:127]
	v_mfma_f32_16x16x32_bf16 v[120:123], v[166:169], v[190:193], v[120:123]
	v_mfma_f32_16x16x32_bf16 v[108:111], v[148:151], v[198:201], v[108:111]
	v_mfma_f32_16x16x32_bf16 v[104:107], v[166:169], v[198:201], v[104:107]
	v_mfma_f32_16x16x32_bf16 v[92:95], v[148:151], v[206:209], v[92:95]
	v_mfma_f32_16x16x32_bf16 v[88:91], v[166:169], v[206:209], v[88:91]
	v_mfma_f32_16x16x32_bf16 v[76:79], v[148:151], v[214:217], v[76:79]
	v_mfma_f32_16x16x32_bf16 v[72:75], v[166:169], v[214:217], v[72:75]
	v_mfma_f32_16x16x32_bf16 v[116:119], v[170:173], v[186:189], v[116:119]
	v_mfma_f32_16x16x32_bf16 v[112:115], v[178:181], v[186:189], v[112:115]
	v_mfma_f32_16x16x32_bf16 v[100:103], v[170:173], v[194:197], v[100:103]
	v_mfma_f32_16x16x32_bf16 v[96:99], v[178:181], v[194:197], v[96:99]
	v_mfma_f32_16x16x32_bf16 v[84:87], v[170:173], v[202:205], v[84:87]
	v_mfma_f32_16x16x32_bf16 v[80:83], v[178:181], v[202:205], v[80:83]
	v_mfma_f32_16x16x32_bf16 v[68:71], v[170:173], v[210:213], v[68:71]
	v_mfma_f32_16x16x32_bf16 v[64:67], v[178:181], v[210:213], v[64:67]
	v_mfma_f32_16x16x32_bf16 v[116:119], v[174:177], v[190:193], v[116:119]
	v_mfma_f32_16x16x32_bf16 v[112:115], v[182:185], v[190:193], v[112:115]
	v_mfma_f32_16x16x32_bf16 v[100:103], v[174:177], v[198:201], v[100:103]
	v_mfma_f32_16x16x32_bf16 v[96:99], v[182:185], v[198:201], v[96:99]
	v_mfma_f32_16x16x32_bf16 v[84:87], v[174:177], v[206:209], v[84:87]
	v_mfma_f32_16x16x32_bf16 v[80:83], v[182:185], v[206:209], v[80:83]
	v_mfma_f32_16x16x32_bf16 v[68:71], v[174:177], v[214:217], v[68:71]
	v_mfma_f32_16x16x32_bf16 v[64:67], v[182:185], v[214:217], v[64:67]
	s_barrier
	s_add_i32 s50, s64, s21
	v_lshl_add_u64 v[152:153], v[152:153], 0, s[30:31]
	s_mov_b32 m0, s50
	s_nop 0
	global_load_lds_dwordx4 v[152:153], off
	s_add_i32 m0, s50, 0x2000
	s_add_u32 s48, s48, 0x80080
	v_lshl_add_u64 v[152:153], v[218:219], 0, s[30:31]
	s_addc_u32 s49, s49, 0
	s_add_i32 s50, s65, s21
	global_load_lds_dwordx4 v[152:153], off
	v_lshl_add_u64 v[152:153], s[48:49], 0, v[130:131]
	s_mov_b32 m0, s50
	s_nop 0
	global_load_lds_dwordx4 v[152:153], off
	v_lshl_add_u64 v[152:153], s[48:49], 0, v[134:135]
	s_add_i32 m0, s50, 0x2000
	s_nop 0
	global_load_lds_dwordx4 v[152:153], off
	v_lshl_add_u64 v[152:153], v[220:221], 0, s[30:31]
	s_mov_b32 m0, s26
	s_nop 0
	global_load_lds_dwordx4 v[152:153], off
	v_lshl_add_u64 v[152:153], v[222:223], 0, s[30:31]
	s_mov_b32 m0, s27
	s_nop 0
	global_load_lds_dwordx4 v[152:153], off
	ds_read_b128 v[186:189], v161 offset:49152
	ds_read_b128 v[190:193], v161 offset:50176
	ds_read_b128 v[194:197], v161 offset:51200
	ds_read_b128 v[198:201], v161 offset:52224
	ds_read_b128 v[202:205], v161 offset:53248
	ds_read_b128 v[206:209], v161 offset:54272
	ds_read_b128 v[210:213], v161 offset:55296
	ds_read_b128 v[214:217], v161 offset:56320
	s_waitcnt vmcnt(8)
	s_waitcnt lgkmcnt(0)
	s_barrier
	s_waitcnt lgkmcnt(0)
	v_mfma_f32_16x16x32_bf16 v[60:63], v[144:147], v[186:189], v[60:63]
	v_mfma_f32_16x16x32_bf16 v[56:59], v[162:165], v[186:189], v[56:59]
	v_mfma_f32_16x16x32_bf16 v[44:47], v[144:147], v[194:197], v[44:47]
	v_mfma_f32_16x16x32_bf16 v[40:43], v[162:165], v[194:197], v[40:43]
	v_mfma_f32_16x16x32_bf16 v[28:31], v[144:147], v[202:205], v[28:31]
	v_mfma_f32_16x16x32_bf16 v[24:27], v[162:165], v[202:205], v[24:27]
	v_mfma_f32_16x16x32_bf16 v[12:15], v[144:147], v[210:213], v[12:15]
	v_mfma_f32_16x16x32_bf16 v[8:11], v[162:165], v[210:213], v[8:11]
	v_mfma_f32_16x16x32_bf16 v[60:63], v[148:151], v[190:193], v[60:63]
	v_mfma_f32_16x16x32_bf16 v[56:59], v[166:169], v[190:193], v[56:59]
	v_mfma_f32_16x16x32_bf16 v[44:47], v[148:151], v[198:201], v[44:47]
	v_mfma_f32_16x16x32_bf16 v[40:43], v[166:169], v[198:201], v[40:43]
	v_mfma_f32_16x16x32_bf16 v[28:31], v[148:151], v[206:209], v[28:31]
	v_mfma_f32_16x16x32_bf16 v[24:27], v[166:169], v[206:209], v[24:27]
	v_mfma_f32_16x16x32_bf16 v[12:15], v[148:151], v[214:217], v[12:15]
	v_mfma_f32_16x16x32_bf16 v[8:11], v[166:169], v[214:217], v[8:11]
	v_mfma_f32_16x16x32_bf16 v[52:55], v[170:173], v[186:189], v[52:55]
	v_mfma_f32_16x16x32_bf16 v[48:51], v[178:181], v[186:189], v[48:51]
	v_mfma_f32_16x16x32_bf16 v[36:39], v[170:173], v[194:197], v[36:39]
	v_mfma_f32_16x16x32_bf16 v[32:35], v[178:181], v[194:197], v[32:35]
	v_mfma_f32_16x16x32_bf16 v[20:23], v[170:173], v[202:205], v[20:23]
	v_mfma_f32_16x16x32_bf16 v[16:19], v[178:181], v[202:205], v[16:19]
	v_mfma_f32_16x16x32_bf16 v[4:7], v[170:173], v[210:213], v[4:7]
	v_mfma_f32_16x16x32_bf16 v[0:3], v[178:181], v[210:213], v[0:3]
	v_mfma_f32_16x16x32_bf16 v[52:55], v[174:177], v[190:193], v[52:55]
	v_mfma_f32_16x16x32_bf16 v[48:51], v[182:185], v[190:193], v[48:51]
	v_mfma_f32_16x16x32_bf16 v[36:39], v[174:177], v[198:201], v[36:39]
	v_mfma_f32_16x16x32_bf16 v[32:35], v[182:185], v[198:201], v[32:35]
	v_mfma_f32_16x16x32_bf16 v[20:23], v[174:177], v[206:209], v[20:23]
	v_mfma_f32_16x16x32_bf16 v[16:19], v[182:185], v[206:209], v[16:19]
	v_mfma_f32_16x16x32_bf16 v[4:7], v[174:177], v[214:217], v[4:7]
	v_mfma_f32_16x16x32_bf16 v[0:3], v[182:185], v[214:217], v[0:3]
	s_barrier
	s_add_i32 s63, s63, 2
	s_add_u32 s46, s46, 0x100
	s_addc_u32 s47, s47, 0
	s_add_u32 s45, s45, 0x100
	s_addc_u32 s62, s62, 0
	s_cmp_gt_u32 s63, 29
	s_cbranch_scc0 .LBB0_1117
	s_setprio 0
	s_and_b64 vcc, exec, s[16:17]
	s_cbranch_vccz .LBB0_1120
	s_barrier

.LBB0_1239:
	s_ashr_i32 s29, s28, 31
	s_lshl_b64 s[30:31], s[28:29], 20
	s_add_u32 s30, s23, s30
	s_addc_u32 s31, s26, s31
	s_and_b64 s[34:35], s[2:3], exec
	s_cselect_b32 s29, s31, s39
	s_cselect_b32 s57, s30, s38
	s_ashr_i32 s19, s18, 31
	s_lshl_b64 s[34:35], s[18:19], 20
	s_add_u32 s34, s27, s34
	s_addc_u32 s35, s46, s35
	s_and_b64 s[42:43], s[2:3], exec
	s_cselect_b32 s19, s35, s41
	s_cselect_b32 s58, s34, s40
	s_add_u32 s59, s40, 0x100
	v_mov_b32_e32 v0, 0
	s_addc_u32 s60, s41, 0
	s_mov_b32 s61, -2
	v_mov_b32_e32 v1, v0
	v_mov_b32_e32 v2, v0
	v_mov_b32_e32 v3, v0
	v_mov_b32_e32 v4, v0
	v_mov_b32_e32 v5, v0
	v_mov_b32_e32 v6, v0
	v_mov_b32_e32 v7, v0
	v_mov_b32_e32 v16, v0
	v_mov_b32_e32 v17, v0
	v_mov_b32_e32 v18, v0
	v_mov_b32_e32 v19, v0
	v_mov_b32_e32 v20, v0
	v_mov_b32_e32 v21, v0
	v_mov_b32_e32 v22, v0
	v_mov_b32_e32 v23, v0
	v_mov_b32_e32 v32, v0
	v_mov_b32_e32 v33, v0
	v_mov_b32_e32 v34, v0
	v_mov_b32_e32 v35, v0
	v_mov_b32_e32 v36, v0
	v_mov_b32_e32 v37, v0
	v_mov_b32_e32 v38, v0
	v_mov_b32_e32 v39, v0
	v_mov_b32_e32 v48, v0
	v_mov_b32_e32 v49, v0
	v_mov_b32_e32 v50, v0
	v_mov_b32_e32 v51, v0
	v_mov_b32_e32 v52, v0
	v_mov_b32_e32 v53, v0
	v_mov_b32_e32 v54, v0
	v_mov_b32_e32 v55, v0
	v_mov_b32_e32 v8, v0
	v_mov_b32_e32 v9, v0
	v_mov_b32_e32 v10, v0
	v_mov_b32_e32 v11, v0
	v_mov_b32_e32 v12, v0
	v_mov_b32_e32 v13, v0
	v_mov_b32_e32 v14, v0
	v_mov_b32_e32 v15, v0
	v_mov_b32_e32 v24, v0
	v_mov_b32_e32 v25, v0
	v_mov_b32_e32 v26, v0
	v_mov_b32_e32 v27, v0
	v_mov_b32_e32 v28, v0
	v_mov_b32_e32 v29, v0
	v_mov_b32_e32 v30, v0
	v_mov_b32_e32 v31, v0
	v_mov_b32_e32 v40, v0
	v_mov_b32_e32 v41, v0
	v_mov_b32_e32 v42, v0
	v_mov_b32_e32 v43, v0
	v_mov_b32_e32 v44, v0
	v_mov_b32_e32 v45, v0
	v_mov_b32_e32 v46, v0
	v_mov_b32_e32 v47, v0
	v_mov_b32_e32 v56, v0
	v_mov_b32_e32 v57, v0
	v_mov_b32_e32 v58, v0
	v_mov_b32_e32 v59, v0
	v_mov_b32_e32 v60, v0
	v_mov_b32_e32 v61, v0
	v_mov_b32_e32 v62, v0
	v_mov_b32_e32 v63, v0
	v_mov_b32_e32 v64, v0
	v_mov_b32_e32 v65, v0
	v_mov_b32_e32 v66, v0
	v_mov_b32_e32 v67, v0
	v_mov_b32_e32 v68, v0
	v_mov_b32_e32 v69, v0
	v_mov_b32_e32 v70, v0
	v_mov_b32_e32 v71, v0
	v_mov_b32_e32 v80, v0
	v_mov_b32_e32 v81, v0
	v_mov_b32_e32 v82, v0
	v_mov_b32_e32 v83, v0
	v_mov_b32_e32 v84, v0
	v_mov_b32_e32 v85, v0
	v_mov_b32_e32 v86, v0
	v_mov_b32_e32 v87, v0
	v_mov_b32_e32 v96, v0
	v_mov_b32_e32 v97, v0
	v_mov_b32_e32 v98, v0
	v_mov_b32_e32 v99, v0
	v_mov_b32_e32 v100, v0
	v_mov_b32_e32 v101, v0
	v_mov_b32_e32 v102, v0
	v_mov_b32_e32 v103, v0
	v_mov_b32_e32 v112, v0
	v_mov_b32_e32 v113, v0
	v_mov_b32_e32 v114, v0
	v_mov_b32_e32 v115, v0
	v_mov_b32_e32 v116, v0
	v_mov_b32_e32 v117, v0
	v_mov_b32_e32 v118, v0
	v_mov_b32_e32 v119, v0
	v_mov_b32_e32 v72, v0
	v_mov_b32_e32 v73, v0
	v_mov_b32_e32 v74, v0
	v_mov_b32_e32 v75, v0
	v_mov_b32_e32 v76, v0
	v_mov_b32_e32 v77, v0
	v_mov_b32_e32 v78, v0
	v_mov_b32_e32 v79, v0
	v_mov_b32_e32 v88, v0
	v_mov_b32_e32 v89, v0
	v_mov_b32_e32 v90, v0
	v_mov_b32_e32 v91, v0
	v_mov_b32_e32 v92, v0
	v_mov_b32_e32 v93, v0
	v_mov_b32_e32 v94, v0
	v_mov_b32_e32 v95, v0
	v_mov_b32_e32 v104, v0
	v_mov_b32_e32 v105, v0
	v_mov_b32_e32 v106, v0
	v_mov_b32_e32 v107, v0
	v_mov_b32_e32 v108, v0
	v_mov_b32_e32 v109, v0
	v_mov_b32_e32 v110, v0
	v_mov_b32_e32 v111, v0
	v_mov_b32_e32 v120, v0
	v_mov_b32_e32 v121, v0
	v_mov_b32_e32 v122, v0
	v_mov_b32_e32 v123, v0
	v_mov_b32_e32 v124, v0
	v_mov_b32_e32 v125, v0
	v_mov_b32_e32 v126, v0
	v_mov_b32_e32 v127, v0
	s_cmp_lt_u32 s97, 4
	s_cbranch_scc1 .Lgprio4
	s_setprio 1
.Lgprio4:
.LBB0_1240:
	ds_read_b128 v[144:147], v153
	ds_read_b128 v[158:161], v153 offset:1024
	ds_read_b128 v[162:165], v153 offset:2048
	ds_read_b128 v[166:169], v153 offset:3072
	ds_read_b128 v[170:173], v154
	ds_read_b128 v[174:177], v154 offset:1024
	ds_read_b128 v[178:181], v154 offset:2048
	ds_read_b128 v[182:185], v154 offset:3072
	s_add_u32 s40, s38, 0x100
	s_addc_u32 s41, s39, 0
	s_cmp_eq_u32 s61, 28
	s_cselect_b32 s45, s29, s41
	s_cselect_b32 s44, s57, s40
	s_cselect_b32 s43, s19, s60
	s_cselect_b32 s42, s58, s59
	v_lshl_add_u64 v[148:149], s[38:39], 0, v[136:137]
	s_add_i32 m0, s37, 0xc000
	s_nop 0
	global_load_lds_dwordx4 v[148:149], off
	v_lshl_add_u64 v[148:149], s[38:39], 0, v[138:139]
	s_add_i32 m0, s37, 0xe000
	s_nop 0
	global_load_lds_dwordx4 v[148:149], off
	ds_read_b128 v[186:189], v155
	ds_read_b128 v[190:193], v155 offset:1024
	ds_read_b128 v[194:197], v155 offset:2048
	ds_read_b128 v[198:201], v155 offset:3072
	ds_read_b128 v[202:205], v155 offset:4096
	ds_read_b128 v[206:209], v155 offset:5120
	ds_read_b128 v[210:213], v155 offset:6144
	ds_read_b128 v[214:217], v155 offset:7168
	s_waitcnt vmcnt(8)
	s_waitcnt lgkmcnt(0)
	s_barrier
	s_waitcnt lgkmcnt(0)
	v_mfma_f32_16x16x32_bf16 v[124:127], v[144:147], v[186:189], v[124:127]
	v_mfma_f32_16x16x32_bf16 v[120:123], v[162:165], v[186:189], v[120:123]
	v_mfma_f32_16x16x32_bf16 v[108:111], v[144:147], v[194:197], v[108:111]
	v_mfma_f32_16x16x32_bf16 v[104:107], v[162:165], v[194:197], v[104:107]
	v_mfma_f32_16x16x32_bf16 v[92:95], v[144:147], v[202:205], v[92:95]
	v_mfma_f32_16x16x32_bf16 v[88:91], v[162:165], v[202:205], v[88:91]
	v_mfma_f32_16x16x32_bf16 v[76:79], v[144:147], v[210:213], v[76:79]
	v_mfma_f32_16x16x32_bf16 v[72:75], v[162:165], v[210:213], v[72:75]
	v_mfma_f32_16x16x32_bf16 v[124:127], v[158:161], v[190:193], v[124:127]
	v_mfma_f32_16x16x32_bf16 v[120:123], v[166:169], v[190:193], v[120:123]
	v_mfma_f32_16x16x32_bf16 v[108:111], v[158:161], v[198:201], v[108:111]
	v_mfma_f32_16x16x32_bf16 v[104:107], v[166:169], v[198:201], v[104:107]
	v_mfma_f32_16x16x32_bf16 v[92:95], v[158:161], v[206:209], v[92:95]
	v_mfma_f32_16x16x32_bf16 v[88:91], v[166:169], v[206:209], v[88:91]
	v_mfma_f32_16x16x32_bf16 v[76:79], v[158:161], v[214:217], v[76:79]
	v_mfma_f32_16x16x32_bf16 v[72:75], v[166:169], v[214:217], v[72:75]
	v_mfma_f32_16x16x32_bf16 v[116:119], v[170:173], v[186:189], v[116:119]
	v_mfma_f32_16x16x32_bf16 v[112:115], v[178:181], v[186:189], v[112:115]
	v_mfma_f32_16x16x32_bf16 v[100:103], v[170:173], v[194:197], v[100:103]
	v_mfma_f32_16x16x32_bf16 v[96:99], v[178:181], v[194:197], v[96:99]
	v_mfma_f32_16x16x32_bf16 v[84:87], v[170:173], v[202:205], v[84:87]
	v_mfma_f32_16x16x32_bf16 v[80:83], v[178:181], v[202:205], v[80:83]
	v_mfma_f32_16x16x32_bf16 v[68:71], v[170:173], v[210:213], v[68:71]
	v_mfma_f32_16x16x32_bf16 v[64:67], v[178:181], v[210:213], v[64:67]
	v_mfma_f32_16x16x32_bf16 v[116:119], v[174:177], v[190:193], v[116:119]
	v_mfma_f32_16x16x32_bf16 v[112:115], v[182:185], v[190:193], v[112:115]
	v_mfma_f32_16x16x32_bf16 v[100:103], v[174:177], v[198:201], v[100:103]
	v_mfma_f32_16x16x32_bf16 v[96:99], v[182:185], v[198:201], v[96:99]
	v_mfma_f32_16x16x32_bf16 v[84:87], v[174:177], v[206:209], v[84:87]
	v_mfma_f32_16x16x32_bf16 v[80:83], v[182:185], v[206:209], v[80:83]
	v_mfma_f32_16x16x32_bf16 v[68:71], v[174:177], v[214:217], v[68:71]
	v_mfma_f32_16x16x32_bf16 v[64:67], v[182:185], v[214:217], v[64:67]
	s_barrier
	s_add_i32 s38, s54, s21
	v_lshl_add_u64 v[148:149], s[42:43], 0, v[132:133]
	s_mov_b32 m0, s38
	v_lshl_add_u64 v[218:219], s[42:43], 0, v[128:129]
	global_load_lds_dwordx4 v[148:149], off
	s_add_i32 m0, s38, 0x2000
	s_add_u32 s38, s42, 0x80000
	s_addc_u32 s39, s43, 0
	s_add_i32 s62, s55, s21
	global_load_lds_dwordx4 v[218:219], off
	v_lshl_add_u64 v[186:187], s[38:39], 0, v[132:133]
	s_mov_b32 m0, s62
	v_lshl_add_u64 v[220:221], s[44:45], 0, v[134:135]
	global_load_lds_dwordx4 v[186:187], off
	v_lshl_add_u64 v[186:187], s[38:39], 0, v[128:129]
	s_add_i32 m0, s62, 0x2000
	v_lshl_add_u64 v[222:223], s[44:45], 0, v[130:131]
	global_load_lds_dwordx4 v[186:187], off
	s_mov_b32 m0, s37
	s_nop 0
	global_load_lds_dwordx4 v[220:221], off
	s_mov_b32 m0, s47
	s_nop 0
	global_load_lds_dwordx4 v[222:223], off
	ds_read_b128 v[186:189], v155 offset:16384
	ds_read_b128 v[190:193], v155 offset:17408
	ds_read_b128 v[194:197], v155 offset:18432
	ds_read_b128 v[198:201], v155 offset:19456
	ds_read_b128 v[202:205], v155 offset:20480
	ds_read_b128 v[206:209], v155 offset:21504
	ds_read_b128 v[210:213], v155 offset:22528
	ds_read_b128 v[214:217], v155 offset:23552
	s_waitcnt vmcnt(8)
	s_waitcnt lgkmcnt(0)
	s_barrier
	s_waitcnt lgkmcnt(0)
	v_mfma_f32_16x16x32_bf16 v[60:63], v[144:147], v[186:189], v[60:63]
	v_mfma_f32_16x16x32_bf16 v[56:59], v[162:165], v[186:189], v[56:59]
	v_mfma_f32_16x16x32_bf16 v[44:47], v[144:147], v[194:197], v[44:47]
	v_mfma_f32_16x16x32_bf16 v[40:43], v[162:165], v[194:197], v[40:43]
	v_mfma_f32_16x16x32_bf16 v[28:31], v[144:147], v[202:205], v[28:31]
	v_mfma_f32_16x16x32_bf16 v[24:27], v[162:165], v[202:205], v[24:27]
	v_mfma_f32_16x16x32_bf16 v[12:15], v[144:147], v[210:213], v[12:15]
	v_mfma_f32_16x16x32_bf16 v[8:11], v[162:165], v[210:213], v[8:11]
	v_mfma_f32_16x16x32_bf16 v[60:63], v[158:161], v[190:193], v[60:63]
	v_mfma_f32_16x16x32_bf16 v[56:59], v[166:169], v[190:193], v[56:59]
	v_mfma_f32_16x16x32_bf16 v[44:47], v[158:161], v[198:201], v[44:47]
	v_mfma_f32_16x16x32_bf16 v[40:43], v[166:169], v[198:201], v[40:43]
	v_mfma_f32_16x16x32_bf16 v[28:31], v[158:161], v[206:209], v[28:31]
	v_mfma_f32_16x16x32_bf16 v[24:27], v[166:169], v[206:209], v[24:27]
	v_mfma_f32_16x16x32_bf16 v[12:15], v[158:161], v[214:217], v[12:15]
	v_mfma_f32_16x16x32_bf16 v[8:11], v[166:169], v[214:217], v[8:11]
	v_mfma_f32_16x16x32_bf16 v[52:55], v[170:173], v[186:189], v[52:55]
	v_mfma_f32_16x16x32_bf16 v[48:51], v[178:181], v[186:189], v[48:51]
	v_mfma_f32_16x16x32_bf16 v[36:39], v[170:173], v[194:197], v[36:39]
	v_mfma_f32_16x16x32_bf16 v[32:35], v[178:181], v[194:197], v[32:35]
	v_mfma_f32_16x16x32_bf16 v[20:23], v[170:173], v[202:205], v[20:23]
	v_mfma_f32_16x16x32_bf16 v[16:19], v[178:181], v[202:205], v[16:19]
	v_mfma_f32_16x16x32_bf16 v[4:7], v[170:173], v[210:213], v[4:7]
	v_mfma_f32_16x16x32_bf16 v[0:3], v[178:181], v[210:213], v[0:3]
	v_mfma_f32_16x16x32_bf16 v[52:55], v[174:177], v[190:193], v[52:55]
	v_mfma_f32_16x16x32_bf16 v[48:51], v[182:185], v[190:193], v[48:51]
	v_mfma_f32_16x16x32_bf16 v[36:39], v[174:177], v[198:201], v[36:39]
	v_mfma_f32_16x16x32_bf16 v[32:35], v[182:185], v[198:201], v[32:35]
	v_mfma_f32_16x16x32_bf16 v[20:23], v[174:177], v[206:209], v[20:23]
	v_mfma_f32_16x16x32_bf16 v[16:19], v[182:185], v[206:209], v[16:19]
	v_mfma_f32_16x16x32_bf16 v[4:7], v[174:177], v[214:217], v[4:7]
	v_mfma_f32_16x16x32_bf16 v[0:3], v[182:185], v[214:217], v[0:3]
	s_barrier
	s_add_i32 s62, 0, 0x18000
	v_add_u32_e32 v157, s62, v150
	s_add_i32 s63, 0, 0x1c000
	ds_read_b128 v[144:147], v157
	ds_read_b128 v[158:161], v157 offset:1024
	ds_read_b128 v[162:165], v157 offset:2048
	ds_read_b128 v[166:169], v157 offset:3072
	v_add_u32_e32 v157, s63, v150
	ds_read_b128 v[170:173], v157
	ds_read_b128 v[174:177], v157 offset:1024
	ds_read_b128 v[178:181], v157 offset:2048
	ds_read_b128 v[182:185], v157 offset:3072
	s_add_u32 s38, s44, 0x80000
	s_addc_u32 s39, s45, 0
	s_mov_b32 m0, s48
	v_lshl_add_u64 v[186:187], s[38:39], 0, v[134:135]
	global_load_lds_dwordx4 v[186:187], off
	v_lshl_add_u64 v[186:187], s[38:39], 0, v[130:131]
	s_mov_b32 m0, s49
	s_nop 0
	global_load_lds_dwordx4 v[186:187], off
	ds_read_b128 v[186:189], v155 offset:32768
	ds_read_b128 v[190:193], v155 offset:33792
	ds_read_b128 v[194:197], v155 offset:34816
	ds_read_b128 v[198:201], v155 offset:35840
	ds_read_b128 v[202:205], v155 offset:36864
	ds_read_b128 v[206:209], v155 offset:37888
	ds_read_b128 v[210:213], v155 offset:38912
	ds_read_b128 v[214:217], v155 offset:39936
	s_waitcnt vmcnt(8)
	s_waitcnt lgkmcnt(0)
	s_barrier
	s_waitcnt lgkmcnt(0)
	v_mfma_f32_16x16x32_bf16 v[124:127], v[144:147], v[186:189], v[124:127]
	v_mfma_f32_16x16x32_bf16 v[120:123], v[162:165], v[186:189], v[120:123]
	v_mfma_f32_16x16x32_bf16 v[108:111], v[144:147], v[194:197], v[108:111]
	v_mfma_f32_16x16x32_bf16 v[104:107], v[162:165], v[194:197], v[104:107]
	v_mfma_f32_16x16x32_bf16 v[92:95], v[144:147], v[202:205], v[92:95]
	v_mfma_f32_16x16x32_bf16 v[88:91], v[162:165], v[202:205], v[88:91]
	v_mfma_f32_16x16x32_bf16 v[76:79], v[144:147], v[210:213], v[76:79]
	v_mfma_f32_16x16x32_bf16 v[72:75], v[162:165], v[210:213], v[72:75]
	v_mfma_f32_16x16x32_bf16 v[124:127], v[158:161], v[190:193], v[124:127]
	v_mfma_f32_16x16x32_bf16 v[120:123], v[166:169], v[190:193], v[120:123]
	v_mfma_f32_16x16x32_bf16 v[108:111], v[158:161], v[198:201], v[108:111]
	v_mfma_f32_16x16x32_bf16 v[104:107], v[166:169], v[198:201], v[104:107]
	v_mfma_f32_16x16x32_bf16 v[92:95], v[158:161], v[206:209], v[92:95]
	v_mfma_f32_16x16x32_bf16 v[88:91], v[166:169], v[206:209], v[88:91]
	v_mfma_f32_16x16x32_bf16 v[76:79], v[158:161], v[214:217], v[76:79]
	v_mfma_f32_16x16x32_bf16 v[72:75], v[166:169], v[214:217], v[72:75]
	v_mfma_f32_16x16x32_bf16 v[116:119], v[170:173], v[186:189], v[116:119]
	v_mfma_f32_16x16x32_bf16 v[112:115], v[178:181], v[186:189], v[112:115]
	v_mfma_f32_16x16x32_bf16 v[100:103], v[170:173], v[194:197], v[100:103]
	v_mfma_f32_16x16x32_bf16 v[96:99], v[178:181], v[194:197], v[96:99]
	v_mfma_f32_16x16x32_bf16 v[84:87], v[170:173], v[202:205], v[84:87]
	v_mfma_f32_16x16x32_bf16 v[80:83], v[178:181], v[202:205], v[80:83]
	v_mfma_f32_16x16x32_bf16 v[68:71], v[170:173], v[210:213], v[68:71]
	v_mfma_f32_16x16x32_bf16 v[64:67], v[178:181], v[210:213], v[64:67]
	v_mfma_f32_16x16x32_bf16 v[116:119], v[174:177], v[190:193], v[116:119]
	v_mfma_f32_16x16x32_bf16 v[112:115], v[182:185], v[190:193], v[112:115]
	v_mfma_f32_16x16x32_bf16 v[100:103], v[174:177], v[198:201], v[100:103]
	v_mfma_f32_16x16x32_bf16 v[96:99], v[182:185], v[198:201], v[96:99]
	v_mfma_f32_16x16x32_bf16 v[84:87], v[174:177], v[206:209], v[84:87]
	v_mfma_f32_16x16x32_bf16 v[80:83], v[182:185], v[206:209], v[80:83]
	v_mfma_f32_16x16x32_bf16 v[68:71], v[174:177], v[214:217], v[68:71]
	v_mfma_f32_16x16x32_bf16 v[64:67], v[182:185], v[214:217], v[64:67]
	s_barrier
	s_add_i32 s38, s62, s21
	v_lshl_add_u64 v[148:149], v[148:149], 0, s[16:17]
	s_mov_b32 m0, s38
	s_nop 0
	global_load_lds_dwordx4 v[148:149], off
	s_add_i32 m0, s38, 0x2000
	s_add_u32 s38, s42, 0x80080
	v_lshl_add_u64 v[148:149], v[218:219], 0, s[16:17]
	s_addc_u32 s39, s43, 0
	s_add_i32 s42, s63, s21
	global_load_lds_dwordx4 v[148:149], off
	v_lshl_add_u64 v[148:149], s[38:39], 0, v[132:133]
	s_mov_b32 m0, s42
	s_nop 0
	global_load_lds_dwordx4 v[148:149], off
	v_lshl_add_u64 v[148:149], s[38:39], 0, v[128:129]
	s_add_i32 m0, s42, 0x2000
	s_nop 0
	global_load_lds_dwordx4 v[148:149], off
	v_lshl_add_u64 v[148:149], v[220:221], 0, s[16:17]
	s_mov_b32 m0, s51
	s_nop 0
	global_load_lds_dwordx4 v[148:149], off
	v_lshl_add_u64 v[148:149], v[222:223], 0, s[16:17]
	s_mov_b32 m0, s52
	s_nop 0
	global_load_lds_dwordx4 v[148:149], off
	ds_read_b128 v[186:189], v155 offset:49152
	ds_read_b128 v[190:193], v155 offset:50176
	ds_read_b128 v[194:197], v155 offset:51200
	ds_read_b128 v[198:201], v155 offset:52224
	ds_read_b128 v[202:205], v155 offset:53248
	ds_read_b128 v[206:209], v155 offset:54272
	ds_read_b128 v[210:213], v155 offset:55296
	ds_read_b128 v[214:217], v155 offset:56320
	s_waitcnt vmcnt(8)
	s_waitcnt lgkmcnt(0)
	s_barrier
	s_waitcnt lgkmcnt(0)
	v_mfma_f32_16x16x32_bf16 v[60:63], v[144:147], v[186:189], v[60:63]
	v_mfma_f32_16x16x32_bf16 v[56:59], v[162:165], v[186:189], v[56:59]
	v_mfma_f32_16x16x32_bf16 v[44:47], v[144:147], v[194:197], v[44:47]
	v_mfma_f32_16x16x32_bf16 v[40:43], v[162:165], v[194:197], v[40:43]
	v_mfma_f32_16x16x32_bf16 v[28:31], v[144:147], v[202:205], v[28:31]
	v_mfma_f32_16x16x32_bf16 v[24:27], v[162:165], v[202:205], v[24:27]
	v_mfma_f32_16x16x32_bf16 v[12:15], v[144:147], v[210:213], v[12:15]
	v_mfma_f32_16x16x32_bf16 v[8:11], v[162:165], v[210:213], v[8:11]
	v_mfma_f32_16x16x32_bf16 v[60:63], v[158:161], v[190:193], v[60:63]
	v_mfma_f32_16x16x32_bf16 v[56:59], v[166:169], v[190:193], v[56:59]
	v_mfma_f32_16x16x32_bf16 v[44:47], v[158:161], v[198:201], v[44:47]
	v_mfma_f32_16x16x32_bf16 v[40:43], v[166:169], v[198:201], v[40:43]
	v_mfma_f32_16x16x32_bf16 v[28:31], v[158:161], v[206:209], v[28:31]
	v_mfma_f32_16x16x32_bf16 v[24:27], v[166:169], v[206:209], v[24:27]
	v_mfma_f32_16x16x32_bf16 v[12:15], v[158:161], v[214:217], v[12:15]
	v_mfma_f32_16x16x32_bf16 v[8:11], v[166:169], v[214:217], v[8:11]
	v_mfma_f32_16x16x32_bf16 v[52:55], v[170:173], v[186:189], v[52:55]
	v_mfma_f32_16x16x32_bf16 v[48:51], v[178:181], v[186:189], v[48:51]
	v_mfma_f32_16x16x32_bf16 v[36:39], v[170:173], v[194:197], v[36:39]
	v_mfma_f32_16x16x32_bf16 v[32:35], v[178:181], v[194:197], v[32:35]
	v_mfma_f32_16x16x32_bf16 v[20:23], v[170:173], v[202:205], v[20:23]
	v_mfma_f32_16x16x32_bf16 v[16:19], v[178:181], v[202:205], v[16:19]
	v_mfma_f32_16x16x32_bf16 v[4:7], v[170:173], v[210:213], v[4:7]
	v_mfma_f32_16x16x32_bf16 v[0:3], v[178:181], v[210:213], v[0:3]
	v_mfma_f32_16x16x32_bf16 v[52:55], v[174:177], v[190:193], v[52:55]
	v_mfma_f32_16x16x32_bf16 v[48:51], v[182:185], v[190:193], v[48:51]
	v_mfma_f32_16x16x32_bf16 v[36:39], v[174:177], v[198:201], v[36:39]
	v_mfma_f32_16x16x32_bf16 v[32:35], v[182:185], v[198:201], v[32:35]
	v_mfma_f32_16x16x32_bf16 v[20:23], v[174:177], v[206:209], v[20:23]
	v_mfma_f32_16x16x32_bf16 v[16:19], v[182:185], v[206:209], v[16:19]
	v_mfma_f32_16x16x32_bf16 v[4:7], v[174:177], v[214:217], v[4:7]
	v_mfma_f32_16x16x32_bf16 v[0:3], v[182:185], v[214:217], v[0:3]
	s_barrier
	s_add_i32 s61, s61, 2
	s_add_u32 s59, s59, 0x100
	s_addc_u32 s60, s60, 0
	s_cmp_gt_u32 s61, 29
	s_mov_b64 s[38:39], s[40:41]
	s_cbranch_scc0 .LBB0_1240
	s_setprio 0
	s_and_b64 vcc, exec, s[6:7]
	s_cbranch_vccz .LBB0_1243
	s_barrier

.LBB0_1326:
	s_add_u32 s53, s34, 0x100
	v_mov_b32_e32 v0, 0
	s_addc_u32 s54, s35, 0
	s_mov_b32 s55, -2
	v_mov_b32_e32 v1, v0
	v_mov_b32_e32 v2, v0
	v_mov_b32_e32 v3, v0
	v_mov_b32_e32 v4, v0
	v_mov_b32_e32 v5, v0
	v_mov_b32_e32 v6, v0
	v_mov_b32_e32 v7, v0
	v_mov_b32_e32 v16, v0
	v_mov_b32_e32 v17, v0
	v_mov_b32_e32 v18, v0
	v_mov_b32_e32 v19, v0
	v_mov_b32_e32 v20, v0
	v_mov_b32_e32 v21, v0
	v_mov_b32_e32 v22, v0
	v_mov_b32_e32 v23, v0
	v_mov_b32_e32 v32, v0
	v_mov_b32_e32 v33, v0
	v_mov_b32_e32 v34, v0
	v_mov_b32_e32 v35, v0
	v_mov_b32_e32 v36, v0
	v_mov_b32_e32 v37, v0
	v_mov_b32_e32 v38, v0
	v_mov_b32_e32 v39, v0
	v_mov_b32_e32 v48, v0
	v_mov_b32_e32 v49, v0
	v_mov_b32_e32 v50, v0
	v_mov_b32_e32 v51, v0
	v_mov_b32_e32 v52, v0
	v_mov_b32_e32 v53, v0
	v_mov_b32_e32 v54, v0
	v_mov_b32_e32 v55, v0
	v_mov_b32_e32 v8, v0
	v_mov_b32_e32 v9, v0
	v_mov_b32_e32 v10, v0
	v_mov_b32_e32 v11, v0
	v_mov_b32_e32 v12, v0
	v_mov_b32_e32 v13, v0
	v_mov_b32_e32 v14, v0
	v_mov_b32_e32 v15, v0
	v_mov_b32_e32 v24, v0
	v_mov_b32_e32 v25, v0
	v_mov_b32_e32 v26, v0
	v_mov_b32_e32 v27, v0
	v_mov_b32_e32 v28, v0
	v_mov_b32_e32 v29, v0
	v_mov_b32_e32 v30, v0
	v_mov_b32_e32 v31, v0
	v_mov_b32_e32 v40, v0
	v_mov_b32_e32 v41, v0
	v_mov_b32_e32 v42, v0
	v_mov_b32_e32 v43, v0
	v_mov_b32_e32 v44, v0
	v_mov_b32_e32 v45, v0
	v_mov_b32_e32 v46, v0
	v_mov_b32_e32 v47, v0
	v_mov_b32_e32 v56, v0
	v_mov_b32_e32 v57, v0
	v_mov_b32_e32 v58, v0
	v_mov_b32_e32 v59, v0
	v_mov_b32_e32 v60, v0
	v_mov_b32_e32 v61, v0
	v_mov_b32_e32 v62, v0
	v_mov_b32_e32 v63, v0
	v_mov_b32_e32 v64, v0
	v_mov_b32_e32 v65, v0
	v_mov_b32_e32 v66, v0
	v_mov_b32_e32 v67, v0
	v_mov_b32_e32 v68, v0
	v_mov_b32_e32 v69, v0
	v_mov_b32_e32 v70, v0
	v_mov_b32_e32 v71, v0
	v_mov_b32_e32 v80, v0
	v_mov_b32_e32 v81, v0
	v_mov_b32_e32 v82, v0
	v_mov_b32_e32 v83, v0
	v_mov_b32_e32 v84, v0
	v_mov_b32_e32 v85, v0
	v_mov_b32_e32 v86, v0
	v_mov_b32_e32 v87, v0
	v_mov_b32_e32 v96, v0
	v_mov_b32_e32 v97, v0
	v_mov_b32_e32 v98, v0
	v_mov_b32_e32 v99, v0
	v_mov_b32_e32 v100, v0
	v_mov_b32_e32 v101, v0
	v_mov_b32_e32 v102, v0
	v_mov_b32_e32 v103, v0
	v_mov_b32_e32 v112, v0
	v_mov_b32_e32 v113, v0
	v_mov_b32_e32 v114, v0
	v_mov_b32_e32 v115, v0
	v_mov_b32_e32 v116, v0
	v_mov_b32_e32 v117, v0
	v_mov_b32_e32 v118, v0
	v_mov_b32_e32 v119, v0
	v_mov_b32_e32 v72, v0
	v_mov_b32_e32 v73, v0
	v_mov_b32_e32 v74, v0
	v_mov_b32_e32 v75, v0
	v_mov_b32_e32 v76, v0
	v_mov_b32_e32 v77, v0
	v_mov_b32_e32 v78, v0
	v_mov_b32_e32 v79, v0
	v_mov_b32_e32 v88, v0
	v_mov_b32_e32 v89, v0
	v_mov_b32_e32 v90, v0
	v_mov_b32_e32 v91, v0
	v_mov_b32_e32 v92, v0
	v_mov_b32_e32 v93, v0
	v_mov_b32_e32 v94, v0
	v_mov_b32_e32 v95, v0
	v_mov_b32_e32 v104, v0
	v_mov_b32_e32 v105, v0
	v_mov_b32_e32 v106, v0
	v_mov_b32_e32 v107, v0
	v_mov_b32_e32 v108, v0
	v_mov_b32_e32 v109, v0
	v_mov_b32_e32 v110, v0
	v_mov_b32_e32 v111, v0
	v_mov_b32_e32 v120, v0
	v_mov_b32_e32 v121, v0
	v_mov_b32_e32 v122, v0
	v_mov_b32_e32 v123, v0
	v_mov_b32_e32 v124, v0
	v_mov_b32_e32 v125, v0
	v_mov_b32_e32 v126, v0
	v_mov_b32_e32 v127, v0
	s_cmp_lt_u32 s97, 4
	s_cbranch_scc1 .Lgprio5
	s_setprio 1
.Lgprio5:
.LBB0_1327:
	ds_read_b128 v[144:147], v151
	ds_read_b128 v[154:157], v151 offset:1024
	ds_read_b128 v[158:161], v151 offset:2048
	ds_read_b128 v[162:165], v151 offset:3072
	ds_read_b128 v[166:169], v152
	ds_read_b128 v[170:173], v152 offset:1024
	ds_read_b128 v[174:177], v152 offset:2048
	ds_read_b128 v[178:181], v152 offset:3072
	s_add_u32 s34, s30, 0x100
	s_addc_u32 s35, s31, 0
	s_cmpk_eq_i32 s55, 0x54
	s_cselect_b32 s39, s5, s35
	s_cselect_b32 s38, s4, s34
	s_cselect_b32 s37, s29, s54
	s_cselect_b32 s36, s28, s53
	v_lshl_add_u64 v[182:183], s[30:31], 0, v[136:137]
	s_add_i32 m0, s40, 0xc000
	s_nop 0
	global_load_lds_dwordx4 v[182:183], off
	v_lshl_add_u64 v[182:183], s[30:31], 0, v[138:139]
	s_add_i32 m0, s40, 0xe000
	s_nop 0
	global_load_lds_dwordx4 v[182:183], off
	ds_read_b128 v[182:185], v153
	ds_read_b128 v[186:189], v153 offset:1024
	ds_read_b128 v[190:193], v153 offset:2048
	ds_read_b128 v[194:197], v153 offset:3072
	ds_read_b128 v[198:201], v153 offset:4096
	ds_read_b128 v[202:205], v153 offset:5120
	ds_read_b128 v[206:209], v153 offset:6144
	ds_read_b128 v[210:213], v153 offset:7168
	s_waitcnt vmcnt(8)
	s_waitcnt lgkmcnt(0)
	s_barrier
	s_waitcnt lgkmcnt(0)
	v_mfma_f32_16x16x32_bf16 v[124:127], v[144:147], v[182:185], v[124:127]
	v_mfma_f32_16x16x32_bf16 v[120:123], v[158:161], v[182:185], v[120:123]
	v_mfma_f32_16x16x32_bf16 v[108:111], v[144:147], v[190:193], v[108:111]
	v_mfma_f32_16x16x32_bf16 v[104:107], v[158:161], v[190:193], v[104:107]
	v_mfma_f32_16x16x32_bf16 v[92:95], v[144:147], v[198:201], v[92:95]
	v_mfma_f32_16x16x32_bf16 v[88:91], v[158:161], v[198:201], v[88:91]
	v_mfma_f32_16x16x32_bf16 v[76:79], v[144:147], v[206:209], v[76:79]
	v_mfma_f32_16x16x32_bf16 v[72:75], v[158:161], v[206:209], v[72:75]
	v_mfma_f32_16x16x32_bf16 v[124:127], v[154:157], v[186:189], v[124:127]
	v_mfma_f32_16x16x32_bf16 v[120:123], v[162:165], v[186:189], v[120:123]
	v_mfma_f32_16x16x32_bf16 v[108:111], v[154:157], v[194:197], v[108:111]
	v_mfma_f32_16x16x32_bf16 v[104:107], v[162:165], v[194:197], v[104:107]
	v_mfma_f32_16x16x32_bf16 v[92:95], v[154:157], v[202:205], v[92:95]
	v_mfma_f32_16x16x32_bf16 v[88:91], v[162:165], v[202:205], v[88:91]
	v_mfma_f32_16x16x32_bf16 v[76:79], v[154:157], v[210:213], v[76:79]
	v_mfma_f32_16x16x32_bf16 v[72:75], v[162:165], v[210:213], v[72:75]
	v_mfma_f32_16x16x32_bf16 v[116:119], v[166:169], v[182:185], v[116:119]
	v_mfma_f32_16x16x32_bf16 v[112:115], v[174:177], v[182:185], v[112:115]
	v_mfma_f32_16x16x32_bf16 v[100:103], v[166:169], v[190:193], v[100:103]
	v_mfma_f32_16x16x32_bf16 v[96:99], v[174:177], v[190:193], v[96:99]
	v_mfma_f32_16x16x32_bf16 v[84:87], v[166:169], v[198:201], v[84:87]
	v_mfma_f32_16x16x32_bf16 v[80:83], v[174:177], v[198:201], v[80:83]
	v_mfma_f32_16x16x32_bf16 v[68:71], v[166:169], v[206:209], v[68:71]
	v_mfma_f32_16x16x32_bf16 v[64:67], v[174:177], v[206:209], v[64:67]
	v_mfma_f32_16x16x32_bf16 v[116:119], v[170:173], v[186:189], v[116:119]
	v_mfma_f32_16x16x32_bf16 v[112:115], v[178:181], v[186:189], v[112:115]
	v_mfma_f32_16x16x32_bf16 v[100:103], v[170:173], v[194:197], v[100:103]
	v_mfma_f32_16x16x32_bf16 v[96:99], v[178:181], v[194:197], v[96:99]
	v_mfma_f32_16x16x32_bf16 v[84:87], v[170:173], v[202:205], v[84:87]
	v_mfma_f32_16x16x32_bf16 v[80:83], v[178:181], v[202:205], v[80:83]
	v_mfma_f32_16x16x32_bf16 v[68:71], v[170:173], v[210:213], v[68:71]
	v_mfma_f32_16x16x32_bf16 v[64:67], v[178:181], v[210:213], v[64:67]
	s_barrier
	s_add_i32 s30, s48, s23
	v_lshl_add_u64 v[214:215], s[36:37], 0, v[130:131]
	s_mov_b32 m0, s30
	v_lshl_add_u64 v[216:217], s[36:37], 0, v[134:135]
	global_load_lds_dwordx4 v[214:215], off
	s_add_i32 m0, s30, 0x2000
	s_add_u32 s30, s36, 0x160000
	s_addc_u32 s31, s37, 0
	s_add_i32 s56, s49, s23
	global_load_lds_dwordx4 v[216:217], off
	v_lshl_add_u64 v[182:183], s[30:31], 0, v[130:131]
	s_mov_b32 m0, s56
	v_lshl_add_u64 v[218:219], s[38:39], 0, v[128:129]
	global_load_lds_dwordx4 v[182:183], off
	v_lshl_add_u64 v[182:183], s[30:31], 0, v[134:135]
	s_add_i32 m0, s56, 0x2000
	v_lshl_add_u64 v[220:221], s[38:39], 0, v[132:133]
	global_load_lds_dwordx4 v[182:183], off
	s_mov_b32 m0, s40
	s_nop 0
	global_load_lds_dwordx4 v[218:219], off
	s_mov_b32 m0, s41
	s_nop 0
	global_load_lds_dwordx4 v[220:221], off
	ds_read_b128 v[182:185], v153 offset:16384
	ds_read_b128 v[186:189], v153 offset:17408
	ds_read_b128 v[190:193], v153 offset:18432
	ds_read_b128 v[194:197], v153 offset:19456
	ds_read_b128 v[198:201], v153 offset:20480
	ds_read_b128 v[202:205], v153 offset:21504
	ds_read_b128 v[206:209], v153 offset:22528
	ds_read_b128 v[210:213], v153 offset:23552
	s_waitcnt vmcnt(8)
	s_waitcnt lgkmcnt(0)
	s_barrier
	s_waitcnt lgkmcnt(0)
	v_mfma_f32_16x16x32_bf16 v[60:63], v[144:147], v[182:185], v[60:63]
	v_mfma_f32_16x16x32_bf16 v[56:59], v[158:161], v[182:185], v[56:59]
	v_mfma_f32_16x16x32_bf16 v[44:47], v[144:147], v[190:193], v[44:47]
	v_mfma_f32_16x16x32_bf16 v[40:43], v[158:161], v[190:193], v[40:43]
	v_mfma_f32_16x16x32_bf16 v[28:31], v[144:147], v[198:201], v[28:31]
	v_mfma_f32_16x16x32_bf16 v[24:27], v[158:161], v[198:201], v[24:27]
	v_mfma_f32_16x16x32_bf16 v[12:15], v[144:147], v[206:209], v[12:15]
	v_mfma_f32_16x16x32_bf16 v[8:11], v[158:161], v[206:209], v[8:11]
	v_mfma_f32_16x16x32_bf16 v[60:63], v[154:157], v[186:189], v[60:63]
	v_mfma_f32_16x16x32_bf16 v[56:59], v[162:165], v[186:189], v[56:59]
	v_mfma_f32_16x16x32_bf16 v[44:47], v[154:157], v[194:197], v[44:47]
	v_mfma_f32_16x16x32_bf16 v[40:43], v[162:165], v[194:197], v[40:43]
	v_mfma_f32_16x16x32_bf16 v[28:31], v[154:157], v[202:205], v[28:31]
	v_mfma_f32_16x16x32_bf16 v[24:27], v[162:165], v[202:205], v[24:27]
	v_mfma_f32_16x16x32_bf16 v[12:15], v[154:157], v[210:213], v[12:15]
	v_mfma_f32_16x16x32_bf16 v[8:11], v[162:165], v[210:213], v[8:11]
	v_mfma_f32_16x16x32_bf16 v[52:55], v[166:169], v[182:185], v[52:55]
	v_mfma_f32_16x16x32_bf16 v[48:51], v[174:177], v[182:185], v[48:51]
	v_mfma_f32_16x16x32_bf16 v[36:39], v[166:169], v[190:193], v[36:39]
	v_mfma_f32_16x16x32_bf16 v[32:35], v[174:177], v[190:193], v[32:35]
	v_mfma_f32_16x16x32_bf16 v[20:23], v[166:169], v[198:201], v[20:23]
	v_mfma_f32_16x16x32_bf16 v[16:19], v[174:177], v[198:201], v[16:19]
	v_mfma_f32_16x16x32_bf16 v[4:7], v[166:169], v[206:209], v[4:7]
	v_mfma_f32_16x16x32_bf16 v[0:3], v[174:177], v[206:209], v[0:3]
	v_mfma_f32_16x16x32_bf16 v[52:55], v[170:173], v[186:189], v[52:55]
	v_mfma_f32_16x16x32_bf16 v[48:51], v[178:181], v[186:189], v[48:51]
	v_mfma_f32_16x16x32_bf16 v[36:39], v[170:173], v[194:197], v[36:39]
	v_mfma_f32_16x16x32_bf16 v[32:35], v[178:181], v[194:197], v[32:35]
	v_mfma_f32_16x16x32_bf16 v[20:23], v[170:173], v[202:205], v[20:23]
	v_mfma_f32_16x16x32_bf16 v[16:19], v[178:181], v[202:205], v[16:19]
	v_mfma_f32_16x16x32_bf16 v[4:7], v[170:173], v[210:213], v[4:7]
	v_mfma_f32_16x16x32_bf16 v[0:3], v[178:181], v[210:213], v[0:3]
	s_barrier
	s_add_i32 s56, 0, 0x18000
	s_add_i32 s57, 0, 0x1c000
	v_add_u32_e32 v162, s56, v148
	v_add_u32_e32 v178, s57, v148
	ds_read_b128 v[144:147], v162
	ds_read_b128 v[154:157], v162 offset:1024
	ds_read_b128 v[158:161], v162 offset:2048
	ds_read_b128 v[162:165], v162 offset:3072
	ds_read_b128 v[166:169], v178
	ds_read_b128 v[170:173], v178 offset:1024
	ds_read_b128 v[174:177], v178 offset:2048
	ds_read_b128 v[178:181], v178 offset:3072
	s_add_u32 s30, s38, 0x160000
	s_addc_u32 s31, s39, 0
	s_mov_b32 m0, s42
	v_lshl_add_u64 v[182:183], s[30:31], 0, v[128:129]
	global_load_lds_dwordx4 v[182:183], off
	v_lshl_add_u64 v[182:183], s[30:31], 0, v[132:133]
	s_mov_b32 m0, s43
	s_nop 0
	global_load_lds_dwordx4 v[182:183], off
	ds_read_b128 v[182:185], v153 offset:32768
	ds_read_b128 v[186:189], v153 offset:33792
	ds_read_b128 v[190:193], v153 offset:34816
	ds_read_b128 v[194:197], v153 offset:35840
	ds_read_b128 v[198:201], v153 offset:36864
	ds_read_b128 v[202:205], v153 offset:37888
	ds_read_b128 v[206:209], v153 offset:38912
	ds_read_b128 v[210:213], v153 offset:39936
	s_waitcnt vmcnt(8)
	s_waitcnt lgkmcnt(0)
	s_barrier
	s_waitcnt lgkmcnt(0)
	v_mfma_f32_16x16x32_bf16 v[124:127], v[144:147], v[182:185], v[124:127]
	v_mfma_f32_16x16x32_bf16 v[120:123], v[158:161], v[182:185], v[120:123]
	v_mfma_f32_16x16x32_bf16 v[108:111], v[144:147], v[190:193], v[108:111]
	v_mfma_f32_16x16x32_bf16 v[104:107], v[158:161], v[190:193], v[104:107]
	v_mfma_f32_16x16x32_bf16 v[92:95], v[144:147], v[198:201], v[92:95]
	v_mfma_f32_16x16x32_bf16 v[88:91], v[158:161], v[198:201], v[88:91]
	v_mfma_f32_16x16x32_bf16 v[76:79], v[144:147], v[206:209], v[76:79]
	v_mfma_f32_16x16x32_bf16 v[72:75], v[158:161], v[206:209], v[72:75]
	v_mfma_f32_16x16x32_bf16 v[124:127], v[154:157], v[186:189], v[124:127]
	v_mfma_f32_16x16x32_bf16 v[120:123], v[162:165], v[186:189], v[120:123]
	v_mfma_f32_16x16x32_bf16 v[108:111], v[154:157], v[194:197], v[108:111]
	v_mfma_f32_16x16x32_bf16 v[104:107], v[162:165], v[194:197], v[104:107]
	v_mfma_f32_16x16x32_bf16 v[92:95], v[154:157], v[202:205], v[92:95]
	v_mfma_f32_16x16x32_bf16 v[88:91], v[162:165], v[202:205], v[88:91]
	v_mfma_f32_16x16x32_bf16 v[76:79], v[154:157], v[210:213], v[76:79]
	v_mfma_f32_16x16x32_bf16 v[72:75], v[162:165], v[210:213], v[72:75]
	v_mfma_f32_16x16x32_bf16 v[116:119], v[166:169], v[182:185], v[116:119]
	v_mfma_f32_16x16x32_bf16 v[112:115], v[174:177], v[182:185], v[112:115]
	v_mfma_f32_16x16x32_bf16 v[100:103], v[166:169], v[190:193], v[100:103]
	v_mfma_f32_16x16x32_bf16 v[96:99], v[174:177], v[190:193], v[96:99]
	v_mfma_f32_16x16x32_bf16 v[84:87], v[166:169], v[198:201], v[84:87]
	v_mfma_f32_16x16x32_bf16 v[80:83], v[174:177], v[198:201], v[80:83]
	v_mfma_f32_16x16x32_bf16 v[68:71], v[166:169], v[206:209], v[68:71]
	v_mfma_f32_16x16x32_bf16 v[64:67], v[174:177], v[206:209], v[64:67]
	v_mfma_f32_16x16x32_bf16 v[116:119], v[170:173], v[186:189], v[116:119]
	v_mfma_f32_16x16x32_bf16 v[112:115], v[178:181], v[186:189], v[112:115]
	v_mfma_f32_16x16x32_bf16 v[100:103], v[170:173], v[194:197], v[100:103]
	v_mfma_f32_16x16x32_bf16 v[96:99], v[178:181], v[194:197], v[96:99]
	v_mfma_f32_16x16x32_bf16 v[84:87], v[170:173], v[202:205], v[84:87]
	v_mfma_f32_16x16x32_bf16 v[80:83], v[178:181], v[202:205], v[80:83]
	v_mfma_f32_16x16x32_bf16 v[68:71], v[170:173], v[210:213], v[68:71]
	v_mfma_f32_16x16x32_bf16 v[64:67], v[178:181], v[210:213], v[64:67]
	s_barrier
	s_add_i32 s30, s56, s23
	v_lshl_add_u64 v[182:183], v[214:215], 0, s[16:17]
	s_mov_b32 m0, s30
	s_nop 0
	global_load_lds_dwordx4 v[182:183], off
	s_add_i32 m0, s30, 0x2000
	s_add_u32 s30, s36, 0x160080
	v_lshl_add_u64 v[182:183], v[216:217], 0, s[16:17]
	s_addc_u32 s31, s37, 0
	s_add_i32 s36, s57, s23
	global_load_lds_dwordx4 v[182:183], off
	v_lshl_add_u64 v[182:183], s[30:31], 0, v[130:131]
	s_mov_b32 m0, s36
	s_nop 0
	global_load_lds_dwordx4 v[182:183], off
	v_lshl_add_u64 v[182:183], s[30:31], 0, v[134:135]
	s_add_i32 m0, s36, 0x2000
	s_nop 0
	global_load_lds_dwordx4 v[182:183], off
	v_lshl_add_u64 v[182:183], v[218:219], 0, s[16:17]
	s_mov_b32 m0, s45
	s_nop 0
	global_load_lds_dwordx4 v[182:183], off
	v_lshl_add_u64 v[182:183], v[220:221], 0, s[16:17]
	s_mov_b32 m0, s46
	s_nop 0
	global_load_lds_dwordx4 v[182:183], off
	ds_read_b128 v[182:185], v153 offset:49152
	ds_read_b128 v[186:189], v153 offset:50176
	ds_read_b128 v[190:193], v153 offset:51200
	ds_read_b128 v[194:197], v153 offset:52224
	ds_read_b128 v[198:201], v153 offset:53248
	ds_read_b128 v[202:205], v153 offset:54272
	ds_read_b128 v[206:209], v153 offset:55296
	ds_read_b128 v[210:213], v153 offset:56320
	s_waitcnt vmcnt(8)
	s_waitcnt lgkmcnt(0)
	s_barrier
	s_waitcnt lgkmcnt(0)
	v_mfma_f32_16x16x32_bf16 v[60:63], v[144:147], v[182:185], v[60:63]
	v_mfma_f32_16x16x32_bf16 v[56:59], v[158:161], v[182:185], v[56:59]
	v_mfma_f32_16x16x32_bf16 v[44:47], v[144:147], v[190:193], v[44:47]
	v_mfma_f32_16x16x32_bf16 v[40:43], v[158:161], v[190:193], v[40:43]
	v_mfma_f32_16x16x32_bf16 v[28:31], v[144:147], v[198:201], v[28:31]
	v_mfma_f32_16x16x32_bf16 v[24:27], v[158:161], v[198:201], v[24:27]
	v_mfma_f32_16x16x32_bf16 v[12:15], v[144:147], v[206:209], v[12:15]
	v_mfma_f32_16x16x32_bf16 v[8:11], v[158:161], v[206:209], v[8:11]
	v_mfma_f32_16x16x32_bf16 v[60:63], v[154:157], v[186:189], v[60:63]
	v_mfma_f32_16x16x32_bf16 v[56:59], v[162:165], v[186:189], v[56:59]
	v_mfma_f32_16x16x32_bf16 v[44:47], v[154:157], v[194:197], v[44:47]
	v_mfma_f32_16x16x32_bf16 v[40:43], v[162:165], v[194:197], v[40:43]
	v_mfma_f32_16x16x32_bf16 v[28:31], v[154:157], v[202:205], v[28:31]
	v_mfma_f32_16x16x32_bf16 v[24:27], v[162:165], v[202:205], v[24:27]
	v_mfma_f32_16x16x32_bf16 v[12:15], v[154:157], v[210:213], v[12:15]
	v_mfma_f32_16x16x32_bf16 v[8:11], v[162:165], v[210:213], v[8:11]
	v_mfma_f32_16x16x32_bf16 v[52:55], v[166:169], v[182:185], v[52:55]
	v_mfma_f32_16x16x32_bf16 v[48:51], v[174:177], v[182:185], v[48:51]
	v_mfma_f32_16x16x32_bf16 v[36:39], v[166:169], v[190:193], v[36:39]
	v_mfma_f32_16x16x32_bf16 v[32:35], v[174:177], v[190:193], v[32:35]
	v_mfma_f32_16x16x32_bf16 v[20:23], v[166:169], v[198:201], v[20:23]
	v_mfma_f32_16x16x32_bf16 v[16:19], v[174:177], v[198:201], v[16:19]
	v_mfma_f32_16x16x32_bf16 v[4:7], v[166:169], v[206:209], v[4:7]
	v_mfma_f32_16x16x32_bf16 v[0:3], v[174:177], v[206:209], v[0:3]
	v_mfma_f32_16x16x32_bf16 v[52:55], v[170:173], v[186:189], v[52:55]
	v_mfma_f32_16x16x32_bf16 v[48:51], v[178:181], v[186:189], v[48:51]
	v_mfma_f32_16x16x32_bf16 v[36:39], v[170:173], v[194:197], v[36:39]
	v_mfma_f32_16x16x32_bf16 v[32:35], v[178:181], v[194:197], v[32:35]
	v_mfma_f32_16x16x32_bf16 v[20:23], v[170:173], v[202:205], v[20:23]
	v_mfma_f32_16x16x32_bf16 v[16:19], v[178:181], v[202:205], v[16:19]
	v_mfma_f32_16x16x32_bf16 v[4:7], v[170:173], v[210:213], v[4:7]
	v_mfma_f32_16x16x32_bf16 v[0:3], v[178:181], v[210:213], v[0:3]
	s_barrier
	s_add_i32 s55, s55, 2
	s_add_u32 s53, s53, 0x100
	s_addc_u32 s54, s54, 0
	s_cmpk_gt_u32 s55, 0x55
	s_mov_b64 s[30:31], s[34:35]
	s_cbranch_scc0 .LBB0_1327
	s_setprio 0
	s_and_b64 vcc, exec, s[8:9]
	s_cbranch_vccz .LBB0_1330
	s_barrier
